# v30 = v29 + counted split of the staging wait in the MT4 k-loop (vmcnt(6) for the early six, vmcnt(3) before the late six writes)
# speedup vs baseline: 1.0130x; 1.0062x over previous
.LBB0_302:
	ds_read_b128 v[216:219], v176 offset:36864
	ds_read_b128 v[200:203], v188
	ds_read_b128 v[220:223], v176 offset:41472
	ds_read_b128 v[204:207], v188 offset:4608
	ds_read_b128 v[208:211], v188 offset:9216
	ds_read_b128 v[212:215], v187
	s_waitcnt lgkmcnt(4)
	v_mfma_f32_32x32x16_bf16 v[112:127], v[200:203], v[216:219], v[112:127]
	ds_read_b128 v[240:243], v176 offset:36896
	global_load_dwordx4 v[140:143], v190, s[42:43]
	s_waitcnt lgkmcnt(4)
	v_mfma_f32_32x32x16_bf16 v[96:111], v[200:203], v[220:223], v[96:111]
	ds_read_b128 v[224:227], v188 offset:32
	global_load_dwordx4 v[160:163], v191, s[42:43]
	s_waitcnt lgkmcnt(4)
	v_mfma_f32_32x32x16_bf16 v[80:95], v[204:207], v[216:219], v[80:95]
	ds_read_b128 v[244:247], v176 offset:41504
	global_load_dwordx4 v[168:171], v192, s[42:43]
	s_waitcnt lgkmcnt(5)
	v_mfma_f32_32x32x16_bf16 v[64:79], v[204:207], v[220:223], v[64:79]
	ds_read_b128 v[228:231], v188 offset:4640
	global_load_dwordx4 v[172:175], v193, s[42:43]
	s_waitcnt lgkmcnt(5)
	v_mfma_f32_32x32x16_bf16 v[48:63], v[208:211], v[216:219], v[48:63]
	ds_read_b128 v[232:235], v188 offset:9248
	global_load_dwordx4 v[152:155], v196, s[40:41]
	s_waitcnt lgkmcnt(6)
	v_mfma_f32_32x32x16_bf16 v[32:47], v[208:211], v[220:223], v[32:47]
	ds_read_b128 v[236:239], v187 offset:32
	global_load_dwordx4 v[156:159], v197, s[40:41]
	s_add_u32 s40, s40, 0x80
	s_addc_u32 s41, s41, 0
	s_add_u32 s42, s42, 0x80
	s_addc_u32 s43, s43, 0
	s_add_u32 s16, s16, 0x80
	s_waitcnt lgkmcnt(6)
	v_mfma_f32_32x32x16_bf16 v[16:31], v[212:215], v[216:219], v[16:31]
	s_waitcnt lgkmcnt(6)
	v_mfma_f32_32x32x16_bf16 v[0:15], v[212:215], v[220:223], v[0:15]
	s_waitcnt lgkmcnt(4)
	v_mfma_f32_32x32x16_bf16 v[112:127], v[224:227], v[240:243], v[112:127]
	ds_read_b128 v[200:203], v188 offset:64
	s_waitcnt lgkmcnt(4)
	v_mfma_f32_32x32x16_bf16 v[96:111], v[224:227], v[244:247], v[96:111]
	ds_read_b128 v[204:207], v188 offset:4672
	s_waitcnt lgkmcnt(4)
	v_mfma_f32_32x32x16_bf16 v[80:95], v[228:231], v[240:243], v[80:95]
	ds_read_b128 v[208:211], v188 offset:9280
	s_waitcnt lgkmcnt(5)
	v_mfma_f32_32x32x16_bf16 v[64:79], v[228:231], v[244:247], v[64:79]
	ds_read_b128 v[212:215], v187 offset:64
	s_waitcnt lgkmcnt(5)
	v_mfma_f32_32x32x16_bf16 v[48:63], v[232:235], v[240:243], v[48:63]
	ds_read_b128 v[216:219], v176 offset:36928
	s_waitcnt lgkmcnt(6)
	v_mfma_f32_32x32x16_bf16 v[32:47], v[232:235], v[244:247], v[32:47]
	ds_read_b128 v[220:223], v176 offset:41536
	s_waitcnt lgkmcnt(6)
	v_mfma_f32_32x32x16_bf16 v[16:31], v[236:239], v[240:243], v[16:31]
	s_waitcnt lgkmcnt(6)
	v_mfma_f32_32x32x16_bf16 v[0:15], v[236:239], v[244:247], v[0:15]
	s_waitcnt lgkmcnt(1)
	v_mfma_f32_32x32x16_bf16 v[112:127], v[200:203], v[216:219], v[112:127]
	ds_read_b128 v[224:227], v188 offset:96
	s_waitcnt lgkmcnt(1)
	v_mfma_f32_32x32x16_bf16 v[96:111], v[200:203], v[220:223], v[96:111]
	ds_read_b128 v[228:231], v188 offset:4704
	s_waitcnt lgkmcnt(3)
	v_mfma_f32_32x32x16_bf16 v[80:95], v[204:207], v[216:219], v[80:95]
	ds_read_b128 v[232:235], v188 offset:9312
	s_waitcnt lgkmcnt(3)
	v_mfma_f32_32x32x16_bf16 v[64:79], v[204:207], v[220:223], v[64:79]
	ds_read_b128 v[236:239], v187 offset:96
	s_waitcnt lgkmcnt(5)
	v_mfma_f32_32x32x16_bf16 v[48:63], v[208:211], v[216:219], v[48:63]
	ds_read_b128 v[240:243], v176 offset:36960
	s_waitcnt lgkmcnt(5)
	v_mfma_f32_32x32x16_bf16 v[32:47], v[208:211], v[220:223], v[32:47]
	ds_read_b128 v[244:247], v176 offset:41568
	s_waitcnt lgkmcnt(7)
	v_mfma_f32_32x32x16_bf16 v[16:31], v[212:215], v[216:219], v[16:31]
	s_waitcnt lgkmcnt(6)
	v_mfma_f32_32x32x16_bf16 v[0:15], v[212:215], v[220:223], v[0:15]
	s_waitcnt lgkmcnt(0)
	s_barrier
	s_waitcnt vmcnt(6)
	s_waitcnt lgkmcnt(1)
	v_mfma_f32_32x32x16_bf16 v[112:127], v[224:227], v[240:243], v[112:127]
	ds_write_b128 v189, v[164:167]
	ds_write_b128 v189, v[128:131] offset:4608
	s_waitcnt lgkmcnt(2)
	v_mfma_f32_32x32x16_bf16 v[96:111], v[224:227], v[244:247], v[96:111]
	ds_write_b128 v189, v[132:135] offset:9216
	global_load_dwordx4 v[164:167], v190, s[40:41]
	s_waitcnt lgkmcnt(4)
	v_mfma_f32_32x32x16_bf16 v[80:95], v[228:231], v[240:243], v[80:95]
	ds_write_b128 v189, v[136:139] offset:13824
	ds_write_b128 v189, v[144:147] offset:18432
	global_load_dwordx4 v[128:131], v191, s[40:41]
	s_waitcnt lgkmcnt(5)
	v_mfma_f32_32x32x16_bf16 v[64:79], v[228:231], v[244:247], v[64:79]
	ds_write_b128 v189, v[148:151] offset:23040
	global_load_dwordx4 v[132:135], v192, s[40:41]
	s_waitcnt lgkmcnt(7)
	v_mfma_f32_32x32x16_bf16 v[48:63], v[232:235], v[240:243], v[48:63]
	s_waitcnt vmcnt(3)
	ds_write_b128 v189, v[152:155] offset:27648
	ds_write_b128 v189, v[156:159] offset:32256
	global_load_dwordx4 v[136:139], v193, s[40:41]
	s_waitcnt lgkmcnt(8)
	v_mfma_f32_32x32x16_bf16 v[32:47], v[232:235], v[244:247], v[32:47]
	ds_write_b128 v189, v[140:143] offset:36864
	global_load_dwordx4 v[144:147], v194, s[40:41]
	s_waitcnt lgkmcnt(10)
	v_mfma_f32_32x32x16_bf16 v[16:31], v[236:239], v[240:243], v[16:31]
	ds_write_b128 v189, v[160:163] offset:41472
	ds_write_b128 v189, v[168:171] offset:46080
	global_load_dwordx4 v[148:151], v195, s[40:41]
	s_waitcnt lgkmcnt(11)
	v_mfma_f32_32x32x16_bf16 v[0:15], v[236:239], v[244:247], v[0:15]
	ds_write_b128 v189, v[172:175] offset:50688
	s_waitcnt lgkmcnt(0)
	s_barrier
	s_cmpk_lg_i32 s16, 0x780
	s_cbranch_scc1 .LBB0_302
	ds_read_b128 v[216:219], v176 offset:36864
	ds_read_b128 v[200:203], v188
	ds_read_b128 v[220:223], v176 offset:41472
	ds_read_b128 v[204:207], v188 offset:4608
	ds_read_b128 v[208:211], v188 offset:9216
	ds_read_b128 v[212:215], v187
	s_waitcnt lgkmcnt(4)
	v_mfma_f32_32x32x16_bf16 v[112:127], v[200:203], v[216:219], v[112:127]
	ds_read_b128 v[240:243], v176 offset:36896
	s_waitcnt lgkmcnt(4)
	v_mfma_f32_32x32x16_bf16 v[96:111], v[200:203], v[220:223], v[96:111]
	ds_read_b128 v[224:227], v188 offset:32
	s_waitcnt lgkmcnt(4)
	v_mfma_f32_32x32x16_bf16 v[80:95], v[204:207], v[216:219], v[80:95]
	ds_read_b128 v[244:247], v176 offset:41504
	s_waitcnt lgkmcnt(5)
	v_mfma_f32_32x32x16_bf16 v[64:79], v[204:207], v[220:223], v[64:79]
	ds_read_b128 v[228:231], v188 offset:4640
	s_waitcnt lgkmcnt(5)
	v_mfma_f32_32x32x16_bf16 v[48:63], v[208:211], v[216:219], v[48:63]
	ds_read_b128 v[232:235], v188 offset:9248
	s_waitcnt lgkmcnt(6)
	v_mfma_f32_32x32x16_bf16 v[32:47], v[208:211], v[220:223], v[32:47]
	ds_read_b128 v[236:239], v187 offset:32
	s_waitcnt lgkmcnt(6)
	v_mfma_f32_32x32x16_bf16 v[16:31], v[212:215], v[216:219], v[16:31]
	s_waitcnt lgkmcnt(6)
	v_mfma_f32_32x32x16_bf16 v[0:15], v[212:215], v[220:223], v[0:15]
	s_waitcnt lgkmcnt(4)
	v_mfma_f32_32x32x16_bf16 v[112:127], v[224:227], v[240:243], v[112:127]
	ds_read_b128 v[200:203], v188 offset:64
	s_waitcnt lgkmcnt(4)
	v_mfma_f32_32x32x16_bf16 v[96:111], v[224:227], v[244:247], v[96:111]
	ds_read_b128 v[204:207], v188 offset:4672
	s_waitcnt lgkmcnt(4)
	v_mfma_f32_32x32x16_bf16 v[80:95], v[228:231], v[240:243], v[80:95]
	ds_read_b128 v[208:211], v188 offset:9280
	s_waitcnt lgkmcnt(5)
	v_mfma_f32_32x32x16_bf16 v[64:79], v[228:231], v[244:247], v[64:79]
	ds_read_b128 v[212:215], v187 offset:64
	s_waitcnt lgkmcnt(5)
	v_mfma_f32_32x32x16_bf16 v[48:63], v[232:235], v[240:243], v[48:63]
	ds_read_b128 v[216:219], v176 offset:36928
	s_waitcnt lgkmcnt(6)
	v_mfma_f32_32x32x16_bf16 v[32:47], v[232:235], v[244:247], v[32:47]
	ds_read_b128 v[220:223], v176 offset:41536
	s_waitcnt lgkmcnt(6)
	v_mfma_f32_32x32x16_bf16 v[16:31], v[236:239], v[240:243], v[16:31]
	s_waitcnt lgkmcnt(6)
	v_mfma_f32_32x32x16_bf16 v[0:15], v[236:239], v[244:247], v[0:15]
	s_waitcnt lgkmcnt(1)
	v_mfma_f32_32x32x16_bf16 v[112:127], v[200:203], v[216:219], v[112:127]
	ds_read_b128 v[224:227], v188 offset:96
	s_waitcnt lgkmcnt(1)
	v_mfma_f32_32x32x16_bf16 v[96:111], v[200:203], v[220:223], v[96:111]
	ds_read_b128 v[228:231], v188 offset:4704
	s_waitcnt lgkmcnt(3)
	v_mfma_f32_32x32x16_bf16 v[80:95], v[204:207], v[216:219], v[80:95]
	ds_read_b128 v[232:235], v188 offset:9312
	s_waitcnt lgkmcnt(3)
	v_mfma_f32_32x32x16_bf16 v[64:79], v[204:207], v[220:223], v[64:79]
	ds_read_b128 v[236:239], v187 offset:96
	s_waitcnt lgkmcnt(5)
	v_mfma_f32_32x32x16_bf16 v[48:63], v[208:211], v[216:219], v[48:63]
	ds_read_b128 v[240:243], v176 offset:36960
	s_waitcnt lgkmcnt(5)
	v_mfma_f32_32x32x16_bf16 v[32:47], v[208:211], v[220:223], v[32:47]
	ds_read_b128 v[244:247], v176 offset:41568
	s_waitcnt lgkmcnt(7)
	v_mfma_f32_32x32x16_bf16 v[16:31], v[212:215], v[216:219], v[16:31]
	s_waitcnt lgkmcnt(6)
	v_mfma_f32_32x32x16_bf16 v[0:15], v[212:215], v[220:223], v[0:15]
	s_waitcnt lgkmcnt(1)
	v_mfma_f32_32x32x16_bf16 v[112:127], v[224:227], v[240:243], v[112:127]
	s_waitcnt lgkmcnt(0)
	v_mfma_f32_32x32x16_bf16 v[96:111], v[224:227], v[244:247], v[96:111]
	s_waitcnt lgkmcnt(1)
	v_mfma_f32_32x32x16_bf16 v[80:95], v[228:231], v[240:243], v[80:95]
	s_waitcnt lgkmcnt(0)
	v_mfma_f32_32x32x16_bf16 v[64:79], v[228:231], v[244:247], v[64:79]
	s_waitcnt lgkmcnt(1)
	v_mfma_f32_32x32x16_bf16 v[48:63], v[232:235], v[240:243], v[48:63]
	s_waitcnt lgkmcnt(0)
	v_mfma_f32_32x32x16_bf16 v[32:47], v[232:235], v[244:247], v[32:47]
	s_waitcnt lgkmcnt(1)
	v_mfma_f32_32x32x16_bf16 v[16:31], v[236:239], v[240:243], v[16:31]
	s_waitcnt lgkmcnt(0)
	v_mfma_f32_32x32x16_bf16 v[0:15], v[236:239], v[244:247], v[0:15]
	s_waitcnt vmcnt(0)
	s_mul_i32 s44, s12, 0x1240
	s_add_u32 s40, s30, s44
	s_addc_u32 s41, s31, 0
	s_lshl_b32 s44, s8, 1
	s_add_u32 s40, s40, s44
	s_addc_u32 s41, s41, 0
	s_add_u32 s40, s40, 0x7157900
	s_addc_u32 s41, s41, 0
	v_and_b32_e32 v131, 15, v182
	v_lshrrev_b32_e32 v172, 4, v182
	v_lshl_add_u32 v130, v131, 3, s8
	s_movk_i32 s44, 0x920
	v_cmp_gt_u32_e64 s[42:43], s44, v130
	v_mul_u32_u24_e32 v164, 0x1240, v172
	v_lshl_add_u32 v164, v131, 4, v164
	v_add_u32_e32 v165, 0x12400, v164
	v_add_u32_e32 v166, 0x24800, v164
	v_add_u32_e32 v167, 0x36c00, v164
	v_add_u32_e32 v168, 0x92000, v164
	v_add_u32_e32 v169, 0xa4400, v164
	v_add_u32_e32 v170, 0xb6800, v164
	v_add_u32_e32 v171, 0xc8c00, v164
	v_mul_u32_u24_e32 v129, 0x110, v172
	v_lshl_add_u32 v129, v131, 4, v129
	v_lshrrev_b32_e32 v131, 7, v182
	v_bfe_u32 v172, v182, 5, 1
	v_lshlrev_b32_e32 v131, 6, v131
	v_lshl_or_b32 v131, v172, 2, v131
	v_mul_u32_u24_e32 v131, 136, v131
	v_and_b32_e32 v172, 0x5f, v182
	v_add_lshl_u32 v128, v131, v172, 1
	s_barrier
	v_cvt_pk_bf16_f32 v112, v112, v113
	v_cvt_pk_bf16_f32 v114, v114, v115
	v_cvt_pk_bf16_f32 v116, v116, v117
	v_cvt_pk_bf16_f32 v118, v118, v119
	v_cvt_pk_bf16_f32 v120, v120, v121
	v_cvt_pk_bf16_f32 v122, v122, v123
	v_cvt_pk_bf16_f32 v124, v124, v125
	v_cvt_pk_bf16_f32 v126, v126, v127
	v_cvt_pk_bf16_f32 v96, v96, v97
	v_cvt_pk_bf16_f32 v98, v98, v99
	v_cvt_pk_bf16_f32 v100, v100, v101
	v_cvt_pk_bf16_f32 v102, v102, v103
	v_cvt_pk_bf16_f32 v104, v104, v105
	v_cvt_pk_bf16_f32 v106, v106, v107
	v_cvt_pk_bf16_f32 v108, v108, v109
	v_cvt_pk_bf16_f32 v110, v110, v111
	v_cvt_pk_bf16_f32 v80, v80, v81
	v_cvt_pk_bf16_f32 v82, v82, v83
	v_cvt_pk_bf16_f32 v84, v84, v85
	v_cvt_pk_bf16_f32 v86, v86, v87
	v_cvt_pk_bf16_f32 v88, v88, v89
	v_cvt_pk_bf16_f32 v90, v90, v91
	v_cvt_pk_bf16_f32 v92, v92, v93
	v_cvt_pk_bf16_f32 v94, v94, v95
	v_cvt_pk_bf16_f32 v64, v64, v65
	v_cvt_pk_bf16_f32 v66, v66, v67
	v_cvt_pk_bf16_f32 v68, v68, v69
	v_cvt_pk_bf16_f32 v70, v70, v71
	v_cvt_pk_bf16_f32 v72, v72, v73
	v_cvt_pk_bf16_f32 v74, v74, v75
	v_cvt_pk_bf16_f32 v76, v76, v77
	v_cvt_pk_bf16_f32 v78, v78, v79
	ds_write_b16 v128, v112
	ds_write_b16_d16_hi v128, v112 offset:272
	ds_write_b16 v128, v114 offset:544
	ds_write_b16_d16_hi v128, v114 offset:816
	ds_write_b16 v128, v116 offset:2176
	ds_write_b16_d16_hi v128, v116 offset:2448
	ds_write_b16 v128, v118 offset:2720
	ds_write_b16_d16_hi v128, v118 offset:2992
	ds_write_b16 v128, v120 offset:4352
	ds_write_b16_d16_hi v128, v120 offset:4624
	ds_write_b16 v128, v122 offset:4896
	ds_write_b16_d16_hi v128, v122 offset:5168
	ds_write_b16 v128, v124 offset:6528
	ds_write_b16_d16_hi v128, v124 offset:6800
	ds_write_b16 v128, v126 offset:7072
	ds_write_b16_d16_hi v128, v126 offset:7344
	ds_write_b16 v128, v96 offset:64
	ds_write_b16_d16_hi v128, v96 offset:336
	ds_write_b16 v128, v98 offset:608
	ds_write_b16_d16_hi v128, v98 offset:880
	ds_write_b16 v128, v100 offset:2240
	ds_write_b16_d16_hi v128, v100 offset:2512
	ds_write_b16 v128, v102 offset:2784
	ds_write_b16_d16_hi v128, v102 offset:3056
	ds_write_b16 v128, v104 offset:4416
	ds_write_b16_d16_hi v128, v104 offset:4688
	ds_write_b16 v128, v106 offset:4960
	ds_write_b16_d16_hi v128, v106 offset:5232
	ds_write_b16 v128, v108 offset:6592
	ds_write_b16_d16_hi v128, v108 offset:6864
	ds_write_b16 v128, v110 offset:7136
	ds_write_b16_d16_hi v128, v110 offset:7408
	ds_write_b16 v128, v80 offset:8704
	ds_write_b16_d16_hi v128, v80 offset:8976
	ds_write_b16 v128, v82 offset:9248
	ds_write_b16_d16_hi v128, v82 offset:9520
	ds_write_b16 v128, v84 offset:10880
	ds_write_b16_d16_hi v128, v84 offset:11152
	ds_write_b16 v128, v86 offset:11424
	ds_write_b16_d16_hi v128, v86 offset:11696
	ds_write_b16 v128, v88 offset:13056
	ds_write_b16_d16_hi v128, v88 offset:13328
	ds_write_b16 v128, v90 offset:13600
	ds_write_b16_d16_hi v128, v90 offset:13872
	ds_write_b16 v128, v92 offset:15232
	ds_write_b16_d16_hi v128, v92 offset:15504
	ds_write_b16 v128, v94 offset:15776
	ds_write_b16_d16_hi v128, v94 offset:16048
	ds_write_b16 v128, v64 offset:8768
	ds_write_b16_d16_hi v128, v64 offset:9040
	ds_write_b16 v128, v66 offset:9312
	ds_write_b16_d16_hi v128, v66 offset:9584
	ds_write_b16 v128, v68 offset:10944
	ds_write_b16_d16_hi v128, v68 offset:11216
	ds_write_b16 v128, v70 offset:11488
	ds_write_b16_d16_hi v128, v70 offset:11760
	ds_write_b16 v128, v72 offset:13120
	ds_write_b16_d16_hi v128, v72 offset:13392
	ds_write_b16 v128, v74 offset:13664
	ds_write_b16_d16_hi v128, v74 offset:13936
	ds_write_b16 v128, v76 offset:15296
	ds_write_b16_d16_hi v128, v76 offset:15568
	ds_write_b16 v128, v78 offset:15840
	ds_write_b16_d16_hi v128, v78 offset:16112
	s_waitcnt lgkmcnt(0)
	s_barrier
	ds_read_b128 v[132:135], v129
	ds_read_b128 v[136:139], v129 offset:4352
	ds_read_b128 v[140:143], v129 offset:8704
	ds_read_b128 v[144:147], v129 offset:13056
	ds_read_b128 v[148:151], v129 offset:17408
	ds_read_b128 v[152:155], v129 offset:21760
	ds_read_b128 v[156:159], v129 offset:26112
	ds_read_b128 v[160:163], v129 offset:30464
	v_cvt_pk_bf16_f32 v48, v48, v49
	v_cvt_pk_bf16_f32 v50, v50, v51
	v_cvt_pk_bf16_f32 v52, v52, v53
	v_cvt_pk_bf16_f32 v54, v54, v55
	v_cvt_pk_bf16_f32 v56, v56, v57
	v_cvt_pk_bf16_f32 v58, v58, v59
	v_cvt_pk_bf16_f32 v60, v60, v61
	v_cvt_pk_bf16_f32 v62, v62, v63
	v_cvt_pk_bf16_f32 v32, v32, v33
	v_cvt_pk_bf16_f32 v34, v34, v35
	v_cvt_pk_bf16_f32 v36, v36, v37
	v_cvt_pk_bf16_f32 v38, v38, v39
	v_cvt_pk_bf16_f32 v40, v40, v41
	v_cvt_pk_bf16_f32 v42, v42, v43
	v_cvt_pk_bf16_f32 v44, v44, v45
	v_cvt_pk_bf16_f32 v46, v46, v47
	v_cvt_pk_bf16_f32 v16, v16, v17
	v_cvt_pk_bf16_f32 v18, v18, v19
	v_cvt_pk_bf16_f32 v20, v20, v21
	v_cvt_pk_bf16_f32 v22, v22, v23
	v_cvt_pk_bf16_f32 v24, v24, v25
	v_cvt_pk_bf16_f32 v26, v26, v27
	v_cvt_pk_bf16_f32 v28, v28, v29
	v_cvt_pk_bf16_f32 v30, v30, v31
	v_cvt_pk_bf16_f32 v0, v0, v1
	v_cvt_pk_bf16_f32 v2, v2, v3
	v_cvt_pk_bf16_f32 v4, v4, v5
	v_cvt_pk_bf16_f32 v6, v6, v7
	v_cvt_pk_bf16_f32 v8, v8, v9
	v_cvt_pk_bf16_f32 v10, v10, v11
	v_cvt_pk_bf16_f32 v12, v12, v13
	v_cvt_pk_bf16_f32 v14, v14, v15
	s_and_saveexec_b64 s[46:47], s[42:43]
	s_waitcnt lgkmcnt(7)
	global_store_dwordx4 v164, v[132:135], s[40:41]
	s_waitcnt lgkmcnt(6)
	global_store_dwordx4 v165, v[136:139], s[40:41]
	s_waitcnt lgkmcnt(5)
	global_store_dwordx4 v166, v[140:143], s[40:41]
	s_waitcnt lgkmcnt(4)
	global_store_dwordx4 v167, v[144:147], s[40:41]
	s_waitcnt lgkmcnt(3)
	global_store_dwordx4 v168, v[148:151], s[40:41]
	s_waitcnt lgkmcnt(2)
	global_store_dwordx4 v169, v[152:155], s[40:41]
	s_waitcnt lgkmcnt(1)
	global_store_dwordx4 v170, v[156:159], s[40:41]
	s_waitcnt lgkmcnt(0)
	global_store_dwordx4 v171, v[160:163], s[40:41]
	s_or_b64 exec, exec, s[46:47]
	s_barrier
	ds_write_b16 v128, v48
	ds_write_b16_d16_hi v128, v48 offset:272
	ds_write_b16 v128, v50 offset:544
	ds_write_b16_d16_hi v128, v50 offset:816
	ds_write_b16 v128, v52 offset:2176
	ds_write_b16_d16_hi v128, v52 offset:2448
	ds_write_b16 v128, v54 offset:2720
	ds_write_b16_d16_hi v128, v54 offset:2992
	ds_write_b16 v128, v56 offset:4352
	ds_write_b16_d16_hi v128, v56 offset:4624
	ds_write_b16 v128, v58 offset:4896
	ds_write_b16_d16_hi v128, v58 offset:5168
	ds_write_b16 v128, v60 offset:6528
	ds_write_b16_d16_hi v128, v60 offset:6800
	ds_write_b16 v128, v62 offset:7072
	ds_write_b16_d16_hi v128, v62 offset:7344
	ds_write_b16 v128, v32 offset:64
	ds_write_b16_d16_hi v128, v32 offset:336
	ds_write_b16 v128, v34 offset:608
	ds_write_b16_d16_hi v128, v34 offset:880
	ds_write_b16 v128, v36 offset:2240
	ds_write_b16_d16_hi v128, v36 offset:2512
	ds_write_b16 v128, v38 offset:2784
	ds_write_b16_d16_hi v128, v38 offset:3056
	ds_write_b16 v128, v40 offset:4416
	ds_write_b16_d16_hi v128, v40 offset:4688
	ds_write_b16 v128, v42 offset:4960
	ds_write_b16_d16_hi v128, v42 offset:5232
	ds_write_b16 v128, v44 offset:6592
	ds_write_b16_d16_hi v128, v44 offset:6864
	ds_write_b16 v128, v46 offset:7136
	ds_write_b16_d16_hi v128, v46 offset:7408
	ds_write_b16 v128, v16 offset:8704
	ds_write_b16_d16_hi v128, v16 offset:8976
	ds_write_b16 v128, v18 offset:9248
	ds_write_b16_d16_hi v128, v18 offset:9520
	ds_write_b16 v128, v20 offset:10880
	ds_write_b16_d16_hi v128, v20 offset:11152
	ds_write_b16 v128, v22 offset:11424
	ds_write_b16_d16_hi v128, v22 offset:11696
	ds_write_b16 v128, v24 offset:13056
	ds_write_b16_d16_hi v128, v24 offset:13328
	ds_write_b16 v128, v26 offset:13600
	ds_write_b16_d16_hi v128, v26 offset:13872
	ds_write_b16 v128, v28 offset:15232
	ds_write_b16_d16_hi v128, v28 offset:15504
	ds_write_b16 v128, v30 offset:15776
	ds_write_b16_d16_hi v128, v30 offset:16048
	ds_write_b16 v128, v0 offset:8768
	ds_write_b16_d16_hi v128, v0 offset:9040
	ds_write_b16 v128, v2 offset:9312
	ds_write_b16_d16_hi v128, v2 offset:9584
	ds_write_b16 v128, v4 offset:10944
	ds_write_b16_d16_hi v128, v4 offset:11216
	ds_write_b16 v128, v6 offset:11488
	ds_write_b16_d16_hi v128, v6 offset:11760
	ds_write_b16 v128, v8 offset:13120
	ds_write_b16_d16_hi v128, v8 offset:13392
	ds_write_b16 v128, v10 offset:13664
	ds_write_b16_d16_hi v128, v10 offset:13936
	ds_write_b16 v128, v12 offset:15296
	ds_write_b16_d16_hi v128, v12 offset:15568
	ds_write_b16 v128, v14 offset:15840
	ds_write_b16_d16_hi v128, v14 offset:16112
	s_waitcnt lgkmcnt(0)
	s_barrier
	ds_read_b128 v[132:135], v129
	ds_read_b128 v[136:139], v129 offset:4352
	ds_read_b128 v[140:143], v129 offset:8704
	ds_read_b128 v[144:147], v129 offset:13056
	ds_read_b128 v[148:151], v129 offset:17408
	ds_read_b128 v[152:155], v129 offset:21760
	ds_read_b128 v[156:159], v129 offset:26112
	ds_read_b128 v[160:163], v129 offset:30464
	v_add_u32_e32 v164, 0x49000, v164
	v_add_u32_e32 v165, 0x49000, v165
	v_add_u32_e32 v166, 0x49000, v166
	v_add_u32_e32 v167, 0x49000, v167
	v_add_u32_e32 v168, 0x49000, v168
	v_add_u32_e32 v169, 0x49000, v169
	v_add_u32_e32 v170, 0x49000, v170
	v_add_u32_e32 v171, 0x49000, v171
	s_and_saveexec_b64 s[46:47], s[42:43]
	s_waitcnt lgkmcnt(7)
	global_store_dwordx4 v164, v[132:135], s[40:41]
	s_waitcnt lgkmcnt(6)
	global_store_dwordx4 v165, v[136:139], s[40:41]
	s_waitcnt lgkmcnt(5)
	global_store_dwordx4 v166, v[140:143], s[40:41]
	s_waitcnt lgkmcnt(4)
	global_store_dwordx4 v167, v[144:147], s[40:41]
	s_waitcnt lgkmcnt(3)
	global_store_dwordx4 v168, v[148:151], s[40:41]
	s_waitcnt lgkmcnt(2)
	global_store_dwordx4 v169, v[152:155], s[40:41]
	s_waitcnt lgkmcnt(1)
	global_store_dwordx4 v170, v[156:159], s[40:41]
	s_waitcnt lgkmcnt(0)
	global_store_dwordx4 v171, v[160:163], s[40:41]
	s_or_b64 exec, exec, s[46:47]
	s_branch .Lmt4_tail_0

.LBB0_997:
	ds_read_b128 v[216:219], v188 offset:36864
	ds_read_b128 v[200:203], v187
	ds_read_b128 v[220:223], v188 offset:41472
	ds_read_b128 v[204:207], v187 offset:4608
	ds_read_b128 v[208:211], v187 offset:9216
	ds_read_b128 v[212:215], v176
	s_waitcnt lgkmcnt(4)
	v_mfma_f32_32x32x16_bf16 v[112:127], v[200:203], v[216:219], v[112:127]
	ds_read_b128 v[240:243], v188 offset:36896
	global_load_dwordx4 v[152:155], v190, s[40:41]
	s_waitcnt lgkmcnt(4)
	v_mfma_f32_32x32x16_bf16 v[96:111], v[200:203], v[220:223], v[96:111]
	ds_read_b128 v[224:227], v187 offset:32
	global_load_dwordx4 v[164:167], v191, s[40:41]
	s_waitcnt lgkmcnt(4)
	v_mfma_f32_32x32x16_bf16 v[80:95], v[204:207], v[216:219], v[80:95]
	ds_read_b128 v[244:247], v188 offset:41504
	global_load_dwordx4 v[168:171], v192, s[40:41]
	s_waitcnt lgkmcnt(5)
	v_mfma_f32_32x32x16_bf16 v[64:79], v[204:207], v[220:223], v[64:79]
	ds_read_b128 v[228:231], v187 offset:4640
	global_load_dwordx4 v[172:175], v193, s[40:41]
	s_waitcnt lgkmcnt(5)
	v_mfma_f32_32x32x16_bf16 v[48:63], v[208:211], v[216:219], v[48:63]
	ds_read_b128 v[232:235], v187 offset:9248
	global_load_dwordx4 v[148:151], v196, s[38:39]
	s_waitcnt lgkmcnt(6)
	v_mfma_f32_32x32x16_bf16 v[32:47], v[208:211], v[220:223], v[32:47]
	ds_read_b128 v[236:239], v176 offset:32
	global_load_dwordx4 v[156:159], v197, s[38:39]
	s_add_u32 s38, s38, 0x80
	s_addc_u32 s39, s39, 0
	s_add_u32 s40, s40, 0x80
	s_addc_u32 s41, s41, 0
	s_add_u32 s12, s12, 0x80
	s_waitcnt lgkmcnt(6)
	v_mfma_f32_32x32x16_bf16 v[16:31], v[212:215], v[216:219], v[16:31]
	s_waitcnt lgkmcnt(6)
	v_mfma_f32_32x32x16_bf16 v[0:15], v[212:215], v[220:223], v[0:15]
	s_waitcnt lgkmcnt(4)
	v_mfma_f32_32x32x16_bf16 v[112:127], v[224:227], v[240:243], v[112:127]
	ds_read_b128 v[200:203], v187 offset:64
	s_waitcnt lgkmcnt(4)
	v_mfma_f32_32x32x16_bf16 v[96:111], v[224:227], v[244:247], v[96:111]
	ds_read_b128 v[204:207], v187 offset:4672
	s_waitcnt lgkmcnt(4)
	v_mfma_f32_32x32x16_bf16 v[80:95], v[228:231], v[240:243], v[80:95]
	ds_read_b128 v[208:211], v187 offset:9280
	s_waitcnt lgkmcnt(5)
	v_mfma_f32_32x32x16_bf16 v[64:79], v[228:231], v[244:247], v[64:79]
	ds_read_b128 v[212:215], v176 offset:64
	s_waitcnt lgkmcnt(5)
	v_mfma_f32_32x32x16_bf16 v[48:63], v[232:235], v[240:243], v[48:63]
	ds_read_b128 v[216:219], v188 offset:36928
	s_waitcnt lgkmcnt(6)
	v_mfma_f32_32x32x16_bf16 v[32:47], v[232:235], v[244:247], v[32:47]
	ds_read_b128 v[220:223], v188 offset:41536
	s_waitcnt lgkmcnt(6)
	v_mfma_f32_32x32x16_bf16 v[16:31], v[236:239], v[240:243], v[16:31]
	s_waitcnt lgkmcnt(6)
	v_mfma_f32_32x32x16_bf16 v[0:15], v[236:239], v[244:247], v[0:15]
	s_waitcnt lgkmcnt(1)
	v_mfma_f32_32x32x16_bf16 v[112:127], v[200:203], v[216:219], v[112:127]
	ds_read_b128 v[224:227], v187 offset:96
	s_waitcnt lgkmcnt(1)
	v_mfma_f32_32x32x16_bf16 v[96:111], v[200:203], v[220:223], v[96:111]
	ds_read_b128 v[228:231], v187 offset:4704
	s_waitcnt lgkmcnt(3)
	v_mfma_f32_32x32x16_bf16 v[80:95], v[204:207], v[216:219], v[80:95]
	ds_read_b128 v[232:235], v187 offset:9312
	s_waitcnt lgkmcnt(3)
	v_mfma_f32_32x32x16_bf16 v[64:79], v[204:207], v[220:223], v[64:79]
	ds_read_b128 v[236:239], v176 offset:96
	s_waitcnt lgkmcnt(5)
	v_mfma_f32_32x32x16_bf16 v[48:63], v[208:211], v[216:219], v[48:63]
	ds_read_b128 v[240:243], v188 offset:36960
	s_waitcnt lgkmcnt(5)
	v_mfma_f32_32x32x16_bf16 v[32:47], v[208:211], v[220:223], v[32:47]
	ds_read_b128 v[244:247], v188 offset:41568
	s_waitcnt lgkmcnt(7)
	v_mfma_f32_32x32x16_bf16 v[16:31], v[212:215], v[216:219], v[16:31]
	s_waitcnt lgkmcnt(6)
	v_mfma_f32_32x32x16_bf16 v[0:15], v[212:215], v[220:223], v[0:15]
	s_waitcnt lgkmcnt(0)
	s_barrier
	s_waitcnt vmcnt(6)
	s_waitcnt lgkmcnt(1)
	v_mfma_f32_32x32x16_bf16 v[112:127], v[224:227], v[240:243], v[112:127]
	ds_write_b128 v189, v[160:163]
	ds_write_b128 v189, v[128:131] offset:4608
	s_waitcnt lgkmcnt(2)
	v_mfma_f32_32x32x16_bf16 v[96:111], v[224:227], v[244:247], v[96:111]
	ds_write_b128 v189, v[132:135] offset:9216
	global_load_dwordx4 v[160:163], v190, s[38:39]
	s_waitcnt lgkmcnt(4)
	v_mfma_f32_32x32x16_bf16 v[80:95], v[228:231], v[240:243], v[80:95]
	ds_write_b128 v189, v[136:139] offset:13824
	ds_write_b128 v189, v[140:143] offset:18432
	global_load_dwordx4 v[128:131], v191, s[38:39]
	s_waitcnt lgkmcnt(5)
	v_mfma_f32_32x32x16_bf16 v[64:79], v[228:231], v[244:247], v[64:79]
	ds_write_b128 v189, v[144:147] offset:23040
	global_load_dwordx4 v[132:135], v192, s[38:39]
	s_waitcnt lgkmcnt(7)
	v_mfma_f32_32x32x16_bf16 v[48:63], v[232:235], v[240:243], v[48:63]
	s_waitcnt vmcnt(3)
	ds_write_b128 v189, v[148:151] offset:27648
	ds_write_b128 v189, v[156:159] offset:32256
	global_load_dwordx4 v[136:139], v193, s[38:39]
	s_waitcnt lgkmcnt(8)
	v_mfma_f32_32x32x16_bf16 v[32:47], v[232:235], v[244:247], v[32:47]
	ds_write_b128 v189, v[152:155] offset:36864
	global_load_dwordx4 v[140:143], v194, s[38:39]
	s_waitcnt lgkmcnt(10)
	v_mfma_f32_32x32x16_bf16 v[16:31], v[236:239], v[240:243], v[16:31]
	ds_write_b128 v189, v[164:167] offset:41472
	ds_write_b128 v189, v[168:171] offset:46080
	global_load_dwordx4 v[144:147], v195, s[38:39]
	s_waitcnt lgkmcnt(11)
	v_mfma_f32_32x32x16_bf16 v[0:15], v[236:239], v[244:247], v[0:15]
	ds_write_b128 v189, v[172:175] offset:50688
	s_waitcnt lgkmcnt(0)
	s_barrier
	s_cmpk_lg_i32 s12, 0x780
	s_cbranch_scc1 .LBB0_997
	ds_read_b128 v[216:219], v188 offset:36864
	ds_read_b128 v[200:203], v187
	ds_read_b128 v[220:223], v188 offset:41472
	ds_read_b128 v[204:207], v187 offset:4608
	ds_read_b128 v[208:211], v187 offset:9216
	ds_read_b128 v[212:215], v176
	s_waitcnt lgkmcnt(4)
	v_mfma_f32_32x32x16_bf16 v[112:127], v[200:203], v[216:219], v[112:127]
	ds_read_b128 v[240:243], v188 offset:36896
	s_waitcnt lgkmcnt(4)
	v_mfma_f32_32x32x16_bf16 v[96:111], v[200:203], v[220:223], v[96:111]
	ds_read_b128 v[224:227], v187 offset:32
	s_waitcnt lgkmcnt(4)
	v_mfma_f32_32x32x16_bf16 v[80:95], v[204:207], v[216:219], v[80:95]
	ds_read_b128 v[244:247], v188 offset:41504
	s_waitcnt lgkmcnt(5)
	v_mfma_f32_32x32x16_bf16 v[64:79], v[204:207], v[220:223], v[64:79]
	ds_read_b128 v[228:231], v187 offset:4640
	s_waitcnt lgkmcnt(5)
	v_mfma_f32_32x32x16_bf16 v[48:63], v[208:211], v[216:219], v[48:63]
	ds_read_b128 v[232:235], v187 offset:9248
	s_waitcnt lgkmcnt(6)
	v_mfma_f32_32x32x16_bf16 v[32:47], v[208:211], v[220:223], v[32:47]
	ds_read_b128 v[236:239], v176 offset:32
	s_waitcnt lgkmcnt(6)
	v_mfma_f32_32x32x16_bf16 v[16:31], v[212:215], v[216:219], v[16:31]
	s_waitcnt lgkmcnt(6)
	v_mfma_f32_32x32x16_bf16 v[0:15], v[212:215], v[220:223], v[0:15]
	s_waitcnt lgkmcnt(4)
	v_mfma_f32_32x32x16_bf16 v[112:127], v[224:227], v[240:243], v[112:127]
	ds_read_b128 v[200:203], v187 offset:64
	s_waitcnt lgkmcnt(4)
	v_mfma_f32_32x32x16_bf16 v[96:111], v[224:227], v[244:247], v[96:111]
	ds_read_b128 v[204:207], v187 offset:4672
	s_waitcnt lgkmcnt(4)
	v_mfma_f32_32x32x16_bf16 v[80:95], v[228:231], v[240:243], v[80:95]
	ds_read_b128 v[208:211], v187 offset:9280
	s_waitcnt lgkmcnt(5)
	v_mfma_f32_32x32x16_bf16 v[64:79], v[228:231], v[244:247], v[64:79]
	ds_read_b128 v[212:215], v176 offset:64
	s_waitcnt lgkmcnt(5)
	v_mfma_f32_32x32x16_bf16 v[48:63], v[232:235], v[240:243], v[48:63]
	ds_read_b128 v[216:219], v188 offset:36928
	s_waitcnt lgkmcnt(6)
	v_mfma_f32_32x32x16_bf16 v[32:47], v[232:235], v[244:247], v[32:47]
	ds_read_b128 v[220:223], v188 offset:41536
	s_waitcnt lgkmcnt(6)
	v_mfma_f32_32x32x16_bf16 v[16:31], v[236:239], v[240:243], v[16:31]
	s_waitcnt lgkmcnt(6)
	v_mfma_f32_32x32x16_bf16 v[0:15], v[236:239], v[244:247], v[0:15]
	s_waitcnt lgkmcnt(1)
	v_mfma_f32_32x32x16_bf16 v[112:127], v[200:203], v[216:219], v[112:127]
	ds_read_b128 v[224:227], v187 offset:96
	s_waitcnt lgkmcnt(1)
	v_mfma_f32_32x32x16_bf16 v[96:111], v[200:203], v[220:223], v[96:111]
	ds_read_b128 v[228:231], v187 offset:4704
	s_waitcnt lgkmcnt(3)
	v_mfma_f32_32x32x16_bf16 v[80:95], v[204:207], v[216:219], v[80:95]
	ds_read_b128 v[232:235], v187 offset:9312
	s_waitcnt lgkmcnt(3)
	v_mfma_f32_32x32x16_bf16 v[64:79], v[204:207], v[220:223], v[64:79]
	ds_read_b128 v[236:239], v176 offset:96
	s_waitcnt lgkmcnt(5)
	v_mfma_f32_32x32x16_bf16 v[48:63], v[208:211], v[216:219], v[48:63]
	ds_read_b128 v[240:243], v188 offset:36960
	s_waitcnt lgkmcnt(5)
	v_mfma_f32_32x32x16_bf16 v[32:47], v[208:211], v[220:223], v[32:47]
	ds_read_b128 v[244:247], v188 offset:41568
	s_waitcnt lgkmcnt(7)
	v_mfma_f32_32x32x16_bf16 v[16:31], v[212:215], v[216:219], v[16:31]
	s_waitcnt lgkmcnt(6)
	v_mfma_f32_32x32x16_bf16 v[0:15], v[212:215], v[220:223], v[0:15]
	s_waitcnt lgkmcnt(1)
	v_mfma_f32_32x32x16_bf16 v[112:127], v[224:227], v[240:243], v[112:127]
	s_waitcnt lgkmcnt(0)
	v_mfma_f32_32x32x16_bf16 v[96:111], v[224:227], v[244:247], v[96:111]
	s_waitcnt lgkmcnt(1)
	v_mfma_f32_32x32x16_bf16 v[80:95], v[228:231], v[240:243], v[80:95]
	s_waitcnt lgkmcnt(0)
	v_mfma_f32_32x32x16_bf16 v[64:79], v[228:231], v[244:247], v[64:79]
	s_waitcnt lgkmcnt(1)
	v_mfma_f32_32x32x16_bf16 v[48:63], v[232:235], v[240:243], v[48:63]
	s_waitcnt lgkmcnt(0)
	v_mfma_f32_32x32x16_bf16 v[32:47], v[232:235], v[244:247], v[32:47]
	s_waitcnt lgkmcnt(1)
	v_mfma_f32_32x32x16_bf16 v[16:31], v[236:239], v[240:243], v[16:31]
	s_waitcnt lgkmcnt(0)
	v_mfma_f32_32x32x16_bf16 v[0:15], v[236:239], v[244:247], v[0:15]
	s_waitcnt vmcnt(0)
	s_mul_i32 s42, s6, 0x2000
	s_add_u32 s44, s30, s42
	s_addc_u32 s45, s31, 0
	s_lshl_b32 s42, s58, 1
	s_add_u32 s44, s44, s42
	s_addc_u32 s45, s45, 0
	s_add_u32 s44, s44, 0x7157900
	s_addc_u32 s45, s45, 0
	s_mov_b32 s43, 1
	v_max_f32_e32 v112, 0, v112
	v_max_f32_e32 v113, 0, v113
	v_mul_f32_e32 v112, v112, v112
	v_mul_f32_e32 v113, v113, v113
	v_cvt_pk_bf16_f32 v190, v112, v113
	v_max_f32_e32 v114, 0, v114
	v_max_f32_e32 v115, 0, v115
	v_mul_f32_e32 v114, v114, v114
	v_mul_f32_e32 v115, v115, v115
	v_cvt_pk_bf16_f32 v191, v114, v115
	v_max_f32_e32 v116, 0, v116
	v_max_f32_e32 v117, 0, v117
	v_mul_f32_e32 v116, v116, v116
	v_mul_f32_e32 v117, v117, v117
	v_cvt_pk_bf16_f32 v192, v116, v117
	v_max_f32_e32 v118, 0, v118
	v_max_f32_e32 v119, 0, v119
	v_mul_f32_e32 v118, v118, v118
	v_mul_f32_e32 v119, v119, v119
	v_cvt_pk_bf16_f32 v193, v118, v119
	v_max_f32_e32 v120, 0, v120
	v_max_f32_e32 v121, 0, v121
	v_mul_f32_e32 v120, v120, v120
	v_mul_f32_e32 v121, v121, v121
	v_cvt_pk_bf16_f32 v194, v120, v121
	v_max_f32_e32 v122, 0, v122
	v_max_f32_e32 v123, 0, v123
	v_mul_f32_e32 v122, v122, v122
	v_mul_f32_e32 v123, v123, v123
	v_cvt_pk_bf16_f32 v195, v122, v123
	v_max_f32_e32 v124, 0, v124
	v_max_f32_e32 v125, 0, v125
	v_mul_f32_e32 v124, v124, v124
	v_mul_f32_e32 v125, v125, v125
	v_cvt_pk_bf16_f32 v196, v124, v125
	v_max_f32_e32 v126, 0, v126
	v_max_f32_e32 v127, 0, v127
	v_mul_f32_e32 v126, v126, v126
	v_mul_f32_e32 v127, v127, v127
	v_cvt_pk_bf16_f32 v197, v126, v127
	v_max_f32_e32 v96, 0, v96
	v_max_f32_e32 v97, 0, v97
	v_mul_f32_e32 v96, v96, v96
	v_mul_f32_e32 v97, v97, v97
	v_cvt_pk_bf16_f32 v198, v96, v97
	v_max_f32_e32 v98, 0, v98
	v_max_f32_e32 v99, 0, v99
	v_mul_f32_e32 v98, v98, v98
	v_mul_f32_e32 v99, v99, v99
	v_cvt_pk_bf16_f32 v199, v98, v99
	v_max_f32_e32 v100, 0, v100
	v_max_f32_e32 v101, 0, v101
	v_mul_f32_e32 v100, v100, v100
	v_mul_f32_e32 v101, v101, v101
	v_cvt_pk_bf16_f32 v200, v100, v101
	v_max_f32_e32 v102, 0, v102
	v_max_f32_e32 v103, 0, v103
	v_mul_f32_e32 v102, v102, v102
	v_mul_f32_e32 v103, v103, v103
	v_cvt_pk_bf16_f32 v201, v102, v103
	v_max_f32_e32 v104, 0, v104
	v_max_f32_e32 v105, 0, v105
	v_mul_f32_e32 v104, v104, v104
	v_mul_f32_e32 v105, v105, v105
	v_cvt_pk_bf16_f32 v202, v104, v105
	v_max_f32_e32 v106, 0, v106
	v_max_f32_e32 v107, 0, v107
	v_mul_f32_e32 v106, v106, v106
	v_mul_f32_e32 v107, v107, v107
	v_cvt_pk_bf16_f32 v203, v106, v107
	v_max_f32_e32 v108, 0, v108
	v_max_f32_e32 v109, 0, v109
	v_mul_f32_e32 v108, v108, v108
	v_mul_f32_e32 v109, v109, v109
	v_cvt_pk_bf16_f32 v204, v108, v109
	v_max_f32_e32 v110, 0, v110
	v_max_f32_e32 v111, 0, v111
	v_mul_f32_e32 v110, v110, v110
	v_mul_f32_e32 v111, v111, v111
	v_cvt_pk_bf16_f32 v205, v110, v111
	v_max_f32_e32 v80, 0, v80
	v_max_f32_e32 v81, 0, v81
	v_mul_f32_e32 v80, v80, v80
	v_mul_f32_e32 v81, v81, v81
	v_cvt_pk_bf16_f32 v206, v80, v81
	v_max_f32_e32 v82, 0, v82
	v_max_f32_e32 v83, 0, v83
	v_mul_f32_e32 v82, v82, v82
	v_mul_f32_e32 v83, v83, v83
	v_cvt_pk_bf16_f32 v207, v82, v83
	v_max_f32_e32 v84, 0, v84
	v_max_f32_e32 v85, 0, v85
	v_mul_f32_e32 v84, v84, v84
	v_mul_f32_e32 v85, v85, v85
	v_cvt_pk_bf16_f32 v208, v84, v85
	v_max_f32_e32 v86, 0, v86
	v_max_f32_e32 v87, 0, v87
	v_mul_f32_e32 v86, v86, v86
	v_mul_f32_e32 v87, v87, v87
	v_cvt_pk_bf16_f32 v209, v86, v87
	v_max_f32_e32 v88, 0, v88
	v_max_f32_e32 v89, 0, v89
	v_mul_f32_e32 v88, v88, v88
	v_mul_f32_e32 v89, v89, v89
	v_cvt_pk_bf16_f32 v210, v88, v89
	v_max_f32_e32 v90, 0, v90
	v_max_f32_e32 v91, 0, v91
	v_mul_f32_e32 v90, v90, v90
	v_mul_f32_e32 v91, v91, v91
	v_cvt_pk_bf16_f32 v211, v90, v91
	v_max_f32_e32 v92, 0, v92
	v_max_f32_e32 v93, 0, v93
	v_mul_f32_e32 v92, v92, v92
	v_mul_f32_e32 v93, v93, v93
	v_cvt_pk_bf16_f32 v212, v92, v93
	v_max_f32_e32 v94, 0, v94
	v_max_f32_e32 v95, 0, v95
	v_mul_f32_e32 v94, v94, v94
	v_mul_f32_e32 v95, v95, v95
	v_cvt_pk_bf16_f32 v213, v94, v95
	v_max_f32_e32 v64, 0, v64
	v_max_f32_e32 v65, 0, v65
	v_mul_f32_e32 v64, v64, v64
	v_mul_f32_e32 v65, v65, v65
	v_cvt_pk_bf16_f32 v214, v64, v65
	v_max_f32_e32 v66, 0, v66
	v_max_f32_e32 v67, 0, v67
	v_mul_f32_e32 v66, v66, v66
	v_mul_f32_e32 v67, v67, v67
	v_cvt_pk_bf16_f32 v215, v66, v67
	v_max_f32_e32 v68, 0, v68
	v_max_f32_e32 v69, 0, v69
	v_mul_f32_e32 v68, v68, v68
	v_mul_f32_e32 v69, v69, v69
	v_cvt_pk_bf16_f32 v216, v68, v69
	v_max_f32_e32 v70, 0, v70
	v_max_f32_e32 v71, 0, v71
	v_mul_f32_e32 v70, v70, v70
	v_mul_f32_e32 v71, v71, v71
	v_cvt_pk_bf16_f32 v217, v70, v71
	v_max_f32_e32 v72, 0, v72
	v_max_f32_e32 v73, 0, v73
	v_mul_f32_e32 v72, v72, v72
	v_mul_f32_e32 v73, v73, v73
	v_cvt_pk_bf16_f32 v218, v72, v73
	v_max_f32_e32 v74, 0, v74
	v_max_f32_e32 v75, 0, v75
	v_mul_f32_e32 v74, v74, v74
	v_mul_f32_e32 v75, v75, v75
	v_cvt_pk_bf16_f32 v219, v74, v75
	v_max_f32_e32 v76, 0, v76
	v_max_f32_e32 v77, 0, v77
	v_mul_f32_e32 v76, v76, v76
	v_mul_f32_e32 v77, v77, v77
	v_cvt_pk_bf16_f32 v220, v76, v77
	v_max_f32_e32 v78, 0, v78
	v_max_f32_e32 v79, 0, v79
	v_mul_f32_e32 v78, v78, v78
	v_mul_f32_e32 v79, v79, v79
	v_cvt_pk_bf16_f32 v221, v78, v79
	v_max_f32_e32 v48, 0, v48
	v_max_f32_e32 v49, 0, v49
	v_mul_f32_e32 v48, v48, v48
	v_mul_f32_e32 v49, v49, v49
	v_cvt_pk_bf16_f32 v222, v48, v49
	v_max_f32_e32 v50, 0, v50
	v_max_f32_e32 v51, 0, v51
	v_mul_f32_e32 v50, v50, v50
	v_mul_f32_e32 v51, v51, v51
	v_cvt_pk_bf16_f32 v223, v50, v51
	v_max_f32_e32 v52, 0, v52
	v_max_f32_e32 v53, 0, v53
	v_mul_f32_e32 v52, v52, v52
	v_mul_f32_e32 v53, v53, v53
	v_cvt_pk_bf16_f32 v224, v52, v53
	v_max_f32_e32 v54, 0, v54
	v_max_f32_e32 v55, 0, v55
	v_mul_f32_e32 v54, v54, v54
	v_mul_f32_e32 v55, v55, v55
	v_cvt_pk_bf16_f32 v225, v54, v55
	v_max_f32_e32 v56, 0, v56
	v_max_f32_e32 v57, 0, v57
	v_mul_f32_e32 v56, v56, v56
	v_mul_f32_e32 v57, v57, v57
	v_cvt_pk_bf16_f32 v226, v56, v57
	v_max_f32_e32 v58, 0, v58
	v_max_f32_e32 v59, 0, v59
	v_mul_f32_e32 v58, v58, v58
	v_mul_f32_e32 v59, v59, v59
	v_cvt_pk_bf16_f32 v227, v58, v59
	v_max_f32_e32 v60, 0, v60
	v_max_f32_e32 v61, 0, v61
	v_mul_f32_e32 v60, v60, v60
	v_mul_f32_e32 v61, v61, v61
	v_cvt_pk_bf16_f32 v228, v60, v61
	v_max_f32_e32 v62, 0, v62
	v_max_f32_e32 v63, 0, v63
	v_mul_f32_e32 v62, v62, v62
	v_mul_f32_e32 v63, v63, v63
	v_cvt_pk_bf16_f32 v229, v62, v63
	v_max_f32_e32 v32, 0, v32
	v_max_f32_e32 v33, 0, v33
	v_mul_f32_e32 v32, v32, v32
	v_mul_f32_e32 v33, v33, v33
	v_cvt_pk_bf16_f32 v230, v32, v33
	v_max_f32_e32 v34, 0, v34
	v_max_f32_e32 v35, 0, v35
	v_mul_f32_e32 v34, v34, v34
	v_mul_f32_e32 v35, v35, v35
	v_cvt_pk_bf16_f32 v231, v34, v35
	v_max_f32_e32 v36, 0, v36
	v_max_f32_e32 v37, 0, v37
	v_mul_f32_e32 v36, v36, v36
	v_mul_f32_e32 v37, v37, v37
	v_cvt_pk_bf16_f32 v232, v36, v37
	v_max_f32_e32 v38, 0, v38
	v_max_f32_e32 v39, 0, v39
	v_mul_f32_e32 v38, v38, v38
	v_mul_f32_e32 v39, v39, v39
	v_cvt_pk_bf16_f32 v233, v38, v39
	v_max_f32_e32 v40, 0, v40
	v_max_f32_e32 v41, 0, v41
	v_mul_f32_e32 v40, v40, v40
	v_mul_f32_e32 v41, v41, v41
	v_cvt_pk_bf16_f32 v234, v40, v41
	v_max_f32_e32 v42, 0, v42
	v_max_f32_e32 v43, 0, v43
	v_mul_f32_e32 v42, v42, v42
	v_mul_f32_e32 v43, v43, v43
	v_cvt_pk_bf16_f32 v235, v42, v43
	v_max_f32_e32 v44, 0, v44
	v_max_f32_e32 v45, 0, v45
	v_mul_f32_e32 v44, v44, v44
	v_mul_f32_e32 v45, v45, v45
	v_cvt_pk_bf16_f32 v236, v44, v45
	v_max_f32_e32 v46, 0, v46
	v_max_f32_e32 v47, 0, v47
	v_mul_f32_e32 v46, v46, v46
	v_mul_f32_e32 v47, v47, v47
	v_cvt_pk_bf16_f32 v237, v46, v47
	v_max_f32_e32 v16, 0, v16
	v_max_f32_e32 v17, 0, v17
	v_mul_f32_e32 v16, v16, v16
	v_mul_f32_e32 v17, v17, v17
	v_cvt_pk_bf16_f32 v238, v16, v17
	v_max_f32_e32 v18, 0, v18
	v_max_f32_e32 v19, 0, v19
	v_mul_f32_e32 v18, v18, v18
	v_mul_f32_e32 v19, v19, v19
	v_cvt_pk_bf16_f32 v239, v18, v19
	v_max_f32_e32 v20, 0, v20
	v_max_f32_e32 v21, 0, v21
	v_mul_f32_e32 v20, v20, v20
	v_mul_f32_e32 v21, v21, v21
	v_cvt_pk_bf16_f32 v240, v20, v21
	v_max_f32_e32 v22, 0, v22
	v_max_f32_e32 v23, 0, v23
	v_mul_f32_e32 v22, v22, v22
	v_mul_f32_e32 v23, v23, v23
	v_cvt_pk_bf16_f32 v241, v22, v23
	v_max_f32_e32 v24, 0, v24
	v_max_f32_e32 v25, 0, v25
	v_mul_f32_e32 v24, v24, v24
	v_mul_f32_e32 v25, v25, v25
	v_cvt_pk_bf16_f32 v242, v24, v25
	v_max_f32_e32 v26, 0, v26
	v_max_f32_e32 v27, 0, v27
	v_mul_f32_e32 v26, v26, v26
	v_mul_f32_e32 v27, v27, v27
	v_cvt_pk_bf16_f32 v243, v26, v27
	v_max_f32_e32 v28, 0, v28
	v_max_f32_e32 v29, 0, v29
	v_mul_f32_e32 v28, v28, v28
	v_mul_f32_e32 v29, v29, v29
	v_cvt_pk_bf16_f32 v244, v28, v29
	v_max_f32_e32 v30, 0, v30
	v_max_f32_e32 v31, 0, v31
	v_mul_f32_e32 v30, v30, v30
	v_mul_f32_e32 v31, v31, v31
	v_cvt_pk_bf16_f32 v245, v30, v31
	v_max_f32_e32 v0, 0, v0
	v_max_f32_e32 v1, 0, v1
	v_mul_f32_e32 v0, v0, v0
	v_mul_f32_e32 v1, v1, v1
	v_cvt_pk_bf16_f32 v246, v0, v1
	v_max_f32_e32 v2, 0, v2
	v_max_f32_e32 v3, 0, v3
	v_mul_f32_e32 v2, v2, v2
	v_mul_f32_e32 v3, v3, v3
	v_cvt_pk_bf16_f32 v247, v2, v3
	v_max_f32_e32 v4, 0, v4
	v_max_f32_e32 v5, 0, v5
	v_mul_f32_e32 v4, v4, v4
	v_mul_f32_e32 v5, v5, v5
	v_cvt_pk_bf16_f32 v248, v4, v5
	v_max_f32_e32 v6, 0, v6
	v_max_f32_e32 v7, 0, v7
	v_mul_f32_e32 v6, v6, v6
	v_mul_f32_e32 v7, v7, v7
	v_cvt_pk_bf16_f32 v249, v6, v7
	v_max_f32_e32 v8, 0, v8
	v_max_f32_e32 v9, 0, v9
	v_mul_f32_e32 v8, v8, v8
	v_mul_f32_e32 v9, v9, v9
	v_cvt_pk_bf16_f32 v250, v8, v9
	v_max_f32_e32 v10, 0, v10
	v_max_f32_e32 v11, 0, v11
	v_mul_f32_e32 v10, v10, v10
	v_mul_f32_e32 v11, v11, v11
	v_cvt_pk_bf16_f32 v251, v10, v11
	v_max_f32_e32 v12, 0, v12
	v_max_f32_e32 v13, 0, v13
	v_mul_f32_e32 v12, v12, v12
	v_mul_f32_e32 v13, v13, v13
	v_cvt_pk_bf16_f32 v252, v12, v13
	v_max_f32_e32 v14, 0, v14
	v_max_f32_e32 v15, 0, v15
	v_mul_f32_e32 v14, v14, v14
	v_mul_f32_e32 v15, v15, v15
	v_cvt_pk_bf16_f32 v253, v14, v15
	s_add_i32 s57, s57, s22
	s_add_i32 s56, s56, s22
	s_cmpk_lt_u32 s57, 0x240
	s_cbranch_scc1 .LBB0_996
	v_and_b32_e32 v3, 15, v182
	v_lshrrev_b32_e32 v4, 4, v182
	v_mul_u32_u24_e32 v2, 0x2000, v4
	v_lshl_add_u32 v2, v3, 4, v2
	v_mul_u32_u24_e32 v1, 0x110, v4
	v_lshl_add_u32 v1, v3, 4, v1
	v_lshrrev_b32_e32 v3, 7, v182
	v_bfe_u32 v4, v182, 5, 1
	v_lshlrev_b32_e32 v3, 6, v3
	v_lshl_or_b32 v3, v4, 2, v3
	v_mul_u32_u24_e32 v3, 136, v3
	v_and_b32_e32 v4, 0x5f, v182
	v_add_lshl_u32 v0, v3, v4, 1
	s_barrier
	ds_write_b16 v0, v190
	ds_write_b16_d16_hi v0, v190 offset:272
	ds_write_b16 v0, v191 offset:544
	ds_write_b16_d16_hi v0, v191 offset:816
	ds_write_b16 v0, v192 offset:2176
	ds_write_b16_d16_hi v0, v192 offset:2448
	ds_write_b16 v0, v193 offset:2720
	ds_write_b16_d16_hi v0, v193 offset:2992
	ds_write_b16 v0, v194 offset:4352
	ds_write_b16_d16_hi v0, v194 offset:4624
	ds_write_b16 v0, v195 offset:4896
	ds_write_b16_d16_hi v0, v195 offset:5168
	ds_write_b16 v0, v196 offset:6528
	ds_write_b16_d16_hi v0, v196 offset:6800
	ds_write_b16 v0, v197 offset:7072
	ds_write_b16_d16_hi v0, v197 offset:7344
	ds_write_b16 v0, v198 offset:64
	ds_write_b16_d16_hi v0, v198 offset:336
	ds_write_b16 v0, v199 offset:608
	ds_write_b16_d16_hi v0, v199 offset:880
	ds_write_b16 v0, v200 offset:2240
	ds_write_b16_d16_hi v0, v200 offset:2512
	ds_write_b16 v0, v201 offset:2784
	ds_write_b16_d16_hi v0, v201 offset:3056
	ds_write_b16 v0, v202 offset:4416
	ds_write_b16_d16_hi v0, v202 offset:4688
	ds_write_b16 v0, v203 offset:4960
	ds_write_b16_d16_hi v0, v203 offset:5232
	ds_write_b16 v0, v204 offset:6592
	ds_write_b16_d16_hi v0, v204 offset:6864
	ds_write_b16 v0, v205 offset:7136
	ds_write_b16_d16_hi v0, v205 offset:7408
	ds_write_b16 v0, v206 offset:8704
	ds_write_b16_d16_hi v0, v206 offset:8976
	ds_write_b16 v0, v207 offset:9248
	ds_write_b16_d16_hi v0, v207 offset:9520
	ds_write_b16 v0, v208 offset:10880
	ds_write_b16_d16_hi v0, v208 offset:11152
	ds_write_b16 v0, v209 offset:11424
	ds_write_b16_d16_hi v0, v209 offset:11696
	ds_write_b16 v0, v210 offset:13056
	ds_write_b16_d16_hi v0, v210 offset:13328
	ds_write_b16 v0, v211 offset:13600
	ds_write_b16_d16_hi v0, v211 offset:13872
	ds_write_b16 v0, v212 offset:15232
	ds_write_b16_d16_hi v0, v212 offset:15504
	ds_write_b16 v0, v213 offset:15776
	ds_write_b16_d16_hi v0, v213 offset:16048
	ds_write_b16 v0, v214 offset:8768
	ds_write_b16_d16_hi v0, v214 offset:9040
	ds_write_b16 v0, v215 offset:9312
	ds_write_b16_d16_hi v0, v215 offset:9584
	ds_write_b16 v0, v216 offset:10944
	ds_write_b16_d16_hi v0, v216 offset:11216
	ds_write_b16 v0, v217 offset:11488
	ds_write_b16_d16_hi v0, v217 offset:11760
	ds_write_b16 v0, v218 offset:13120
	ds_write_b16_d16_hi v0, v218 offset:13392
	ds_write_b16 v0, v219 offset:13664
	ds_write_b16_d16_hi v0, v219 offset:13936
	ds_write_b16 v0, v220 offset:15296
	ds_write_b16_d16_hi v0, v220 offset:15568
	ds_write_b16 v0, v221 offset:15840
	ds_write_b16_d16_hi v0, v221 offset:16112
	s_waitcnt lgkmcnt(0)
	s_barrier
	ds_read_b128 v[8:11], v1
	ds_read_b128 v[12:15], v1 offset:4352
	ds_read_b128 v[16:19], v1 offset:8704
	ds_read_b128 v[20:23], v1 offset:13056
	ds_read_b128 v[24:27], v1 offset:17408
	ds_read_b128 v[28:31], v1 offset:21760
	ds_read_b128 v[32:35], v1 offset:26112
	ds_read_b128 v[36:39], v1 offset:30464
	s_add_u32 s38, s44, 0x0
	s_addc_u32 s39, s45, 0
	s_waitcnt lgkmcnt(7)
	global_store_dwordx4 v2, v[8:11], s[38:39]
	s_add_u32 s38, s44, 0x20000
	s_addc_u32 s39, s45, 0
	s_waitcnt lgkmcnt(6)
	global_store_dwordx4 v2, v[12:15], s[38:39]
	s_add_u32 s38, s44, 0x40000
	s_addc_u32 s39, s45, 0
	s_waitcnt lgkmcnt(5)
	global_store_dwordx4 v2, v[16:19], s[38:39]
	s_add_u32 s38, s44, 0x60000
	s_addc_u32 s39, s45, 0
	s_waitcnt lgkmcnt(4)
	global_store_dwordx4 v2, v[20:23], s[38:39]
	s_add_u32 s38, s44, 0x100000
	s_addc_u32 s39, s45, 0
	s_waitcnt lgkmcnt(3)
	global_store_dwordx4 v2, v[24:27], s[38:39]
	s_add_u32 s38, s44, 0x120000
	s_addc_u32 s39, s45, 0
	s_waitcnt lgkmcnt(2)
	global_store_dwordx4 v2, v[28:31], s[38:39]
	s_add_u32 s38, s44, 0x140000
	s_addc_u32 s39, s45, 0
	s_waitcnt lgkmcnt(1)
	global_store_dwordx4 v2, v[32:35], s[38:39]
	s_add_u32 s38, s44, 0x160000
	s_addc_u32 s39, s45, 0
	s_waitcnt lgkmcnt(0)
	global_store_dwordx4 v2, v[36:39], s[38:39]
	s_barrier
	ds_write_b16 v0, v222
	ds_write_b16_d16_hi v0, v222 offset:272
	ds_write_b16 v0, v223 offset:544
	ds_write_b16_d16_hi v0, v223 offset:816
	ds_write_b16 v0, v224 offset:2176
	ds_write_b16_d16_hi v0, v224 offset:2448
	ds_write_b16 v0, v225 offset:2720
	ds_write_b16_d16_hi v0, v225 offset:2992
	ds_write_b16 v0, v226 offset:4352
	ds_write_b16_d16_hi v0, v226 offset:4624
	ds_write_b16 v0, v227 offset:4896
	ds_write_b16_d16_hi v0, v227 offset:5168
	ds_write_b16 v0, v228 offset:6528
	ds_write_b16_d16_hi v0, v228 offset:6800
	ds_write_b16 v0, v229 offset:7072
	ds_write_b16_d16_hi v0, v229 offset:7344
	ds_write_b16 v0, v230 offset:64
	ds_write_b16_d16_hi v0, v230 offset:336
	ds_write_b16 v0, v231 offset:608
	ds_write_b16_d16_hi v0, v231 offset:880
	ds_write_b16 v0, v232 offset:2240
	ds_write_b16_d16_hi v0, v232 offset:2512
	ds_write_b16 v0, v233 offset:2784
	ds_write_b16_d16_hi v0, v233 offset:3056
	ds_write_b16 v0, v234 offset:4416
	ds_write_b16_d16_hi v0, v234 offset:4688
	ds_write_b16 v0, v235 offset:4960
	ds_write_b16_d16_hi v0, v235 offset:5232
	ds_write_b16 v0, v236 offset:6592
	ds_write_b16_d16_hi v0, v236 offset:6864
	ds_write_b16 v0, v237 offset:7136
	ds_write_b16_d16_hi v0, v237 offset:7408
	ds_write_b16 v0, v238 offset:8704
	ds_write_b16_d16_hi v0, v238 offset:8976
	ds_write_b16 v0, v239 offset:9248
	ds_write_b16_d16_hi v0, v239 offset:9520
	ds_write_b16 v0, v240 offset:10880
	ds_write_b16_d16_hi v0, v240 offset:11152
	ds_write_b16 v0, v241 offset:11424
	ds_write_b16_d16_hi v0, v241 offset:11696
	ds_write_b16 v0, v242 offset:13056
	ds_write_b16_d16_hi v0, v242 offset:13328
	ds_write_b16 v0, v243 offset:13600
	ds_write_b16_d16_hi v0, v243 offset:13872
	ds_write_b16 v0, v244 offset:15232
	ds_write_b16_d16_hi v0, v244 offset:15504
	ds_write_b16 v0, v245 offset:15776
	ds_write_b16_d16_hi v0, v245 offset:16048
	ds_write_b16 v0, v246 offset:8768
	ds_write_b16_d16_hi v0, v246 offset:9040
	ds_write_b16 v0, v247 offset:9312
	ds_write_b16_d16_hi v0, v247 offset:9584
	ds_write_b16 v0, v248 offset:10944
	ds_write_b16_d16_hi v0, v248 offset:11216
	ds_write_b16 v0, v249 offset:11488
	ds_write_b16_d16_hi v0, v249 offset:11760
	ds_write_b16 v0, v250 offset:13120
	ds_write_b16_d16_hi v0, v250 offset:13392
	ds_write_b16 v0, v251 offset:13664
	ds_write_b16_d16_hi v0, v251 offset:13936
	ds_write_b16 v0, v252 offset:15296
	ds_write_b16_d16_hi v0, v252 offset:15568
	ds_write_b16 v0, v253 offset:15840
	ds_write_b16_d16_hi v0, v253 offset:16112
	s_waitcnt lgkmcnt(0)
	s_barrier
	ds_read_b128 v[8:11], v1
	ds_read_b128 v[12:15], v1 offset:4352
	ds_read_b128 v[16:19], v1 offset:8704
	ds_read_b128 v[20:23], v1 offset:13056
	ds_read_b128 v[24:27], v1 offset:17408
	ds_read_b128 v[28:31], v1 offset:21760
	ds_read_b128 v[32:35], v1 offset:26112
	ds_read_b128 v[36:39], v1 offset:30464
	s_add_u32 s38, s44, 0x80000
	s_addc_u32 s39, s45, 0
	s_waitcnt lgkmcnt(7)
	global_store_dwordx4 v2, v[8:11], s[38:39]
	s_add_u32 s38, s44, 0xa0000
	s_addc_u32 s39, s45, 0
	s_waitcnt lgkmcnt(6)
	global_store_dwordx4 v2, v[12:15], s[38:39]
	s_add_u32 s38, s44, 0xc0000
	s_addc_u32 s39, s45, 0
	s_waitcnt lgkmcnt(5)
	global_store_dwordx4 v2, v[16:19], s[38:39]
	s_add_u32 s38, s44, 0xe0000
	s_addc_u32 s39, s45, 0
	s_waitcnt lgkmcnt(4)
	global_store_dwordx4 v2, v[20:23], s[38:39]
	s_add_u32 s38, s44, 0x180000
	s_addc_u32 s39, s45, 0
	s_waitcnt lgkmcnt(3)
	global_store_dwordx4 v2, v[24:27], s[38:39]
	s_add_u32 s38, s44, 0x1a0000
	s_addc_u32 s39, s45, 0
	s_waitcnt lgkmcnt(2)
	global_store_dwordx4 v2, v[28:31], s[38:39]
	s_add_u32 s38, s44, 0x1c0000
	s_addc_u32 s39, s45, 0
	s_waitcnt lgkmcnt(1)
	global_store_dwordx4 v2, v[32:35], s[38:39]
	s_add_u32 s38, s44, 0x1e0000
	s_addc_u32 s39, s45, 0
	s_waitcnt lgkmcnt(0)
	global_store_dwordx4 v2, v[36:39], s[38:39]
	s_mov_b32 s43, 0
	s_branch .LBB0_989

.LBB0_1284:
	ds_read_b128 v[216:219], v176 offset:36864
	ds_read_b128 v[200:203], v188
	ds_read_b128 v[220:223], v176 offset:41472
	ds_read_b128 v[204:207], v188 offset:4608
	ds_read_b128 v[208:211], v188 offset:9216
	ds_read_b128 v[212:215], v187
	s_waitcnt lgkmcnt(4)
	v_mfma_f32_32x32x16_bf16 v[112:127], v[200:203], v[216:219], v[112:127]
	ds_read_b128 v[240:243], v176 offset:36896
	global_load_dwordx4 v[140:143], v190, s[44:45]
	s_waitcnt lgkmcnt(4)
	v_mfma_f32_32x32x16_bf16 v[96:111], v[200:203], v[220:223], v[96:111]
	ds_read_b128 v[224:227], v188 offset:32
	global_load_dwordx4 v[160:163], v191, s[44:45]
	s_waitcnt lgkmcnt(4)
	v_mfma_f32_32x32x16_bf16 v[80:95], v[204:207], v[216:219], v[80:95]
	ds_read_b128 v[244:247], v176 offset:41504
	global_load_dwordx4 v[168:171], v192, s[44:45]
	s_waitcnt lgkmcnt(5)
	v_mfma_f32_32x32x16_bf16 v[64:79], v[204:207], v[220:223], v[64:79]
	ds_read_b128 v[228:231], v188 offset:4640
	global_load_dwordx4 v[172:175], v193, s[44:45]
	s_waitcnt lgkmcnt(5)
	v_mfma_f32_32x32x16_bf16 v[48:63], v[208:211], v[216:219], v[48:63]
	ds_read_b128 v[232:235], v188 offset:9248
	global_load_dwordx4 v[152:155], v196, s[42:43]
	s_waitcnt lgkmcnt(6)
	v_mfma_f32_32x32x16_bf16 v[32:47], v[208:211], v[220:223], v[32:47]
	ds_read_b128 v[236:239], v187 offset:32
	global_load_dwordx4 v[156:159], v197, s[42:43]
	s_add_u32 s42, s42, 0x80
	s_addc_u32 s43, s43, 0
	s_add_u32 s44, s44, 0x80
	s_addc_u32 s45, s45, 0
	s_add_u32 s16, s16, 0x80
	s_waitcnt lgkmcnt(6)
	v_mfma_f32_32x32x16_bf16 v[16:31], v[212:215], v[216:219], v[16:31]
	s_waitcnt lgkmcnt(6)
	v_mfma_f32_32x32x16_bf16 v[0:15], v[212:215], v[220:223], v[0:15]
	s_waitcnt lgkmcnt(4)
	v_mfma_f32_32x32x16_bf16 v[112:127], v[224:227], v[240:243], v[112:127]
	ds_read_b128 v[200:203], v188 offset:64
	s_waitcnt lgkmcnt(4)
	v_mfma_f32_32x32x16_bf16 v[96:111], v[224:227], v[244:247], v[96:111]
	ds_read_b128 v[204:207], v188 offset:4672
	s_waitcnt lgkmcnt(4)
	v_mfma_f32_32x32x16_bf16 v[80:95], v[228:231], v[240:243], v[80:95]
	ds_read_b128 v[208:211], v188 offset:9280
	s_waitcnt lgkmcnt(5)
	v_mfma_f32_32x32x16_bf16 v[64:79], v[228:231], v[244:247], v[64:79]
	ds_read_b128 v[212:215], v187 offset:64
	s_waitcnt lgkmcnt(5)
	v_mfma_f32_32x32x16_bf16 v[48:63], v[232:235], v[240:243], v[48:63]
	ds_read_b128 v[216:219], v176 offset:36928
	s_waitcnt lgkmcnt(6)
	v_mfma_f32_32x32x16_bf16 v[32:47], v[232:235], v[244:247], v[32:47]
	ds_read_b128 v[220:223], v176 offset:41536
	s_waitcnt lgkmcnt(6)
	v_mfma_f32_32x32x16_bf16 v[16:31], v[236:239], v[240:243], v[16:31]
	s_waitcnt lgkmcnt(6)
	v_mfma_f32_32x32x16_bf16 v[0:15], v[236:239], v[244:247], v[0:15]
	s_waitcnt lgkmcnt(1)
	v_mfma_f32_32x32x16_bf16 v[112:127], v[200:203], v[216:219], v[112:127]
	ds_read_b128 v[224:227], v188 offset:96
	s_waitcnt lgkmcnt(1)
	v_mfma_f32_32x32x16_bf16 v[96:111], v[200:203], v[220:223], v[96:111]
	ds_read_b128 v[228:231], v188 offset:4704
	s_waitcnt lgkmcnt(3)
	v_mfma_f32_32x32x16_bf16 v[80:95], v[204:207], v[216:219], v[80:95]
	ds_read_b128 v[232:235], v188 offset:9312
	s_waitcnt lgkmcnt(3)
	v_mfma_f32_32x32x16_bf16 v[64:79], v[204:207], v[220:223], v[64:79]
	ds_read_b128 v[236:239], v187 offset:96
	s_waitcnt lgkmcnt(5)
	v_mfma_f32_32x32x16_bf16 v[48:63], v[208:211], v[216:219], v[48:63]
	ds_read_b128 v[240:243], v176 offset:36960
	s_waitcnt lgkmcnt(5)
	v_mfma_f32_32x32x16_bf16 v[32:47], v[208:211], v[220:223], v[32:47]
	ds_read_b128 v[244:247], v176 offset:41568
	s_waitcnt lgkmcnt(7)
	v_mfma_f32_32x32x16_bf16 v[16:31], v[212:215], v[216:219], v[16:31]
	s_waitcnt lgkmcnt(6)
	v_mfma_f32_32x32x16_bf16 v[0:15], v[212:215], v[220:223], v[0:15]
	s_waitcnt lgkmcnt(0)
	s_barrier
	s_waitcnt vmcnt(6)
	s_waitcnt lgkmcnt(1)
	v_mfma_f32_32x32x16_bf16 v[112:127], v[224:227], v[240:243], v[112:127]
	ds_write_b128 v189, v[164:167]
	ds_write_b128 v189, v[128:131] offset:4608
	s_waitcnt lgkmcnt(2)
	v_mfma_f32_32x32x16_bf16 v[96:111], v[224:227], v[244:247], v[96:111]
	ds_write_b128 v189, v[132:135] offset:9216
	global_load_dwordx4 v[164:167], v190, s[42:43]
	s_waitcnt lgkmcnt(4)
	v_mfma_f32_32x32x16_bf16 v[80:95], v[228:231], v[240:243], v[80:95]
	ds_write_b128 v189, v[136:139] offset:13824
	ds_write_b128 v189, v[144:147] offset:18432
	global_load_dwordx4 v[128:131], v191, s[42:43]
	s_waitcnt lgkmcnt(5)
	v_mfma_f32_32x32x16_bf16 v[64:79], v[228:231], v[244:247], v[64:79]
	ds_write_b128 v189, v[148:151] offset:23040
	global_load_dwordx4 v[132:135], v192, s[42:43]
	s_waitcnt lgkmcnt(7)
	v_mfma_f32_32x32x16_bf16 v[48:63], v[232:235], v[240:243], v[48:63]
	s_waitcnt vmcnt(3)
	ds_write_b128 v189, v[152:155] offset:27648
	ds_write_b128 v189, v[156:159] offset:32256
	global_load_dwordx4 v[136:139], v193, s[42:43]
	s_waitcnt lgkmcnt(8)
	v_mfma_f32_32x32x16_bf16 v[32:47], v[232:235], v[244:247], v[32:47]
	ds_write_b128 v189, v[140:143] offset:36864
	global_load_dwordx4 v[144:147], v194, s[42:43]
	s_waitcnt lgkmcnt(10)
	v_mfma_f32_32x32x16_bf16 v[16:31], v[236:239], v[240:243], v[16:31]
	ds_write_b128 v189, v[160:163] offset:41472
	ds_write_b128 v189, v[168:171] offset:46080
	global_load_dwordx4 v[148:151], v195, s[42:43]
	s_waitcnt lgkmcnt(11)
	v_mfma_f32_32x32x16_bf16 v[0:15], v[236:239], v[244:247], v[0:15]
	ds_write_b128 v189, v[172:175] offset:50688
	s_waitcnt lgkmcnt(0)
	s_barrier
	s_cmpk_lg_i32 s16, 0x780
	s_cbranch_scc1 .LBB0_1284
	ds_read_b128 v[216:219], v176 offset:36864
	ds_read_b128 v[200:203], v188
	ds_read_b128 v[220:223], v176 offset:41472
	ds_read_b128 v[204:207], v188 offset:4608
	ds_read_b128 v[208:211], v188 offset:9216
	ds_read_b128 v[212:215], v187
	s_waitcnt lgkmcnt(4)
	v_mfma_f32_32x32x16_bf16 v[112:127], v[200:203], v[216:219], v[112:127]
	ds_read_b128 v[240:243], v176 offset:36896
	s_waitcnt lgkmcnt(4)
	v_mfma_f32_32x32x16_bf16 v[96:111], v[200:203], v[220:223], v[96:111]
	ds_read_b128 v[224:227], v188 offset:32
	s_waitcnt lgkmcnt(4)
	v_mfma_f32_32x32x16_bf16 v[80:95], v[204:207], v[216:219], v[80:95]
	ds_read_b128 v[244:247], v176 offset:41504
	s_waitcnt lgkmcnt(5)
	v_mfma_f32_32x32x16_bf16 v[64:79], v[204:207], v[220:223], v[64:79]
	ds_read_b128 v[228:231], v188 offset:4640
	s_waitcnt lgkmcnt(5)
	v_mfma_f32_32x32x16_bf16 v[48:63], v[208:211], v[216:219], v[48:63]
	ds_read_b128 v[232:235], v188 offset:9248
	s_waitcnt lgkmcnt(6)
	v_mfma_f32_32x32x16_bf16 v[32:47], v[208:211], v[220:223], v[32:47]
	ds_read_b128 v[236:239], v187 offset:32
	s_waitcnt lgkmcnt(6)
	v_mfma_f32_32x32x16_bf16 v[16:31], v[212:215], v[216:219], v[16:31]
	s_waitcnt lgkmcnt(6)
	v_mfma_f32_32x32x16_bf16 v[0:15], v[212:215], v[220:223], v[0:15]
	s_waitcnt lgkmcnt(4)
	v_mfma_f32_32x32x16_bf16 v[112:127], v[224:227], v[240:243], v[112:127]
	ds_read_b128 v[200:203], v188 offset:64
	s_waitcnt lgkmcnt(4)
	v_mfma_f32_32x32x16_bf16 v[96:111], v[224:227], v[244:247], v[96:111]
	ds_read_b128 v[204:207], v188 offset:4672
	s_waitcnt lgkmcnt(4)
	v_mfma_f32_32x32x16_bf16 v[80:95], v[228:231], v[240:243], v[80:95]
	ds_read_b128 v[208:211], v188 offset:9280
	s_waitcnt lgkmcnt(5)
	v_mfma_f32_32x32x16_bf16 v[64:79], v[228:231], v[244:247], v[64:79]
	ds_read_b128 v[212:215], v187 offset:64
	s_waitcnt lgkmcnt(5)
	v_mfma_f32_32x32x16_bf16 v[48:63], v[232:235], v[240:243], v[48:63]
	ds_read_b128 v[216:219], v176 offset:36928
	s_waitcnt lgkmcnt(6)
	v_mfma_f32_32x32x16_bf16 v[32:47], v[232:235], v[244:247], v[32:47]
	ds_read_b128 v[220:223], v176 offset:41536
	s_waitcnt lgkmcnt(6)
	v_mfma_f32_32x32x16_bf16 v[16:31], v[236:239], v[240:243], v[16:31]
	s_waitcnt lgkmcnt(6)
	v_mfma_f32_32x32x16_bf16 v[0:15], v[236:239], v[244:247], v[0:15]
	s_waitcnt lgkmcnt(1)
	v_mfma_f32_32x32x16_bf16 v[112:127], v[200:203], v[216:219], v[112:127]
	ds_read_b128 v[224:227], v188 offset:96
	s_waitcnt lgkmcnt(1)
	v_mfma_f32_32x32x16_bf16 v[96:111], v[200:203], v[220:223], v[96:111]
	ds_read_b128 v[228:231], v188 offset:4704
	s_waitcnt lgkmcnt(3)
	v_mfma_f32_32x32x16_bf16 v[80:95], v[204:207], v[216:219], v[80:95]
	ds_read_b128 v[232:235], v188 offset:9312
	s_waitcnt lgkmcnt(3)
	v_mfma_f32_32x32x16_bf16 v[64:79], v[204:207], v[220:223], v[64:79]
	ds_read_b128 v[236:239], v187 offset:96
	s_waitcnt lgkmcnt(5)
	v_mfma_f32_32x32x16_bf16 v[48:63], v[208:211], v[216:219], v[48:63]
	ds_read_b128 v[240:243], v176 offset:36960
	s_waitcnt lgkmcnt(5)
	v_mfma_f32_32x32x16_bf16 v[32:47], v[208:211], v[220:223], v[32:47]
	ds_read_b128 v[244:247], v176 offset:41568
	s_waitcnt lgkmcnt(7)
	v_mfma_f32_32x32x16_bf16 v[16:31], v[212:215], v[216:219], v[16:31]
	s_waitcnt lgkmcnt(6)
	v_mfma_f32_32x32x16_bf16 v[0:15], v[212:215], v[220:223], v[0:15]
	s_waitcnt lgkmcnt(1)
	v_mfma_f32_32x32x16_bf16 v[112:127], v[224:227], v[240:243], v[112:127]
	s_waitcnt lgkmcnt(0)
	v_mfma_f32_32x32x16_bf16 v[96:111], v[224:227], v[244:247], v[96:111]
	s_waitcnt lgkmcnt(1)
	v_mfma_f32_32x32x16_bf16 v[80:95], v[228:231], v[240:243], v[80:95]
	s_waitcnt lgkmcnt(0)
	v_mfma_f32_32x32x16_bf16 v[64:79], v[228:231], v[244:247], v[64:79]
	s_waitcnt lgkmcnt(1)
	v_mfma_f32_32x32x16_bf16 v[48:63], v[232:235], v[240:243], v[48:63]
	s_waitcnt lgkmcnt(0)
	v_mfma_f32_32x32x16_bf16 v[32:47], v[232:235], v[244:247], v[32:47]
	s_waitcnt lgkmcnt(1)
	v_mfma_f32_32x32x16_bf16 v[16:31], v[236:239], v[240:243], v[16:31]
	s_waitcnt lgkmcnt(0)
	v_mfma_f32_32x32x16_bf16 v[0:15], v[236:239], v[244:247], v[0:15]
	s_waitcnt vmcnt(0)
	s_mul_i32 s41, s12, 0x1240
	s_add_u32 s42, s30, s41
	s_addc_u32 s43, s31, 0
	s_lshl_b32 s41, s8, 1
	s_add_u32 s42, s42, s41
	s_addc_u32 s43, s43, 0
	s_add_u32 s42, s42, 0x7157900
	s_addc_u32 s43, s43, 0
	v_and_b32_e32 v131, 15, v182
	v_lshrrev_b32_e32 v172, 4, v182
	v_lshl_add_u32 v130, v131, 3, s8
	s_movk_i32 s41, 0x920
	v_cmp_gt_u32_e64 s[44:45], s41, v130
	v_mul_u32_u24_e32 v164, 0x1240, v172
	v_lshl_add_u32 v164, v131, 4, v164
	v_add_u32_e32 v165, 0x12400, v164
	v_add_u32_e32 v166, 0x24800, v164
	v_add_u32_e32 v167, 0x36c00, v164
	v_add_u32_e32 v168, 0x92000, v164
	v_add_u32_e32 v169, 0xa4400, v164
	v_add_u32_e32 v170, 0xb6800, v164
	v_add_u32_e32 v171, 0xc8c00, v164
	v_mul_u32_u24_e32 v129, 0x110, v172
	v_lshl_add_u32 v129, v131, 4, v129
	v_lshrrev_b32_e32 v131, 7, v182
	v_bfe_u32 v172, v182, 5, 1
	v_lshlrev_b32_e32 v131, 6, v131
	v_lshl_or_b32 v131, v172, 2, v131
	v_mul_u32_u24_e32 v131, 136, v131
	v_and_b32_e32 v172, 0x5f, v182
	v_add_lshl_u32 v128, v131, v172, 1
	s_barrier
	v_cvt_pk_bf16_f32 v112, v112, v113
	v_cvt_pk_bf16_f32 v114, v114, v115
	v_cvt_pk_bf16_f32 v116, v116, v117
	v_cvt_pk_bf16_f32 v118, v118, v119
	v_cvt_pk_bf16_f32 v120, v120, v121
	v_cvt_pk_bf16_f32 v122, v122, v123
	v_cvt_pk_bf16_f32 v124, v124, v125
	v_cvt_pk_bf16_f32 v126, v126, v127
	v_cvt_pk_bf16_f32 v96, v96, v97
	v_cvt_pk_bf16_f32 v98, v98, v99
	v_cvt_pk_bf16_f32 v100, v100, v101
	v_cvt_pk_bf16_f32 v102, v102, v103
	v_cvt_pk_bf16_f32 v104, v104, v105
	v_cvt_pk_bf16_f32 v106, v106, v107
	v_cvt_pk_bf16_f32 v108, v108, v109
	v_cvt_pk_bf16_f32 v110, v110, v111
	v_cvt_pk_bf16_f32 v80, v80, v81
	v_cvt_pk_bf16_f32 v82, v82, v83
	v_cvt_pk_bf16_f32 v84, v84, v85
	v_cvt_pk_bf16_f32 v86, v86, v87
	v_cvt_pk_bf16_f32 v88, v88, v89
	v_cvt_pk_bf16_f32 v90, v90, v91
	v_cvt_pk_bf16_f32 v92, v92, v93
	v_cvt_pk_bf16_f32 v94, v94, v95
	v_cvt_pk_bf16_f32 v64, v64, v65
	v_cvt_pk_bf16_f32 v66, v66, v67
	v_cvt_pk_bf16_f32 v68, v68, v69
	v_cvt_pk_bf16_f32 v70, v70, v71
	v_cvt_pk_bf16_f32 v72, v72, v73
	v_cvt_pk_bf16_f32 v74, v74, v75
	v_cvt_pk_bf16_f32 v76, v76, v77
	v_cvt_pk_bf16_f32 v78, v78, v79
	ds_write_b16 v128, v112
	ds_write_b16_d16_hi v128, v112 offset:272
	ds_write_b16 v128, v114 offset:544
	ds_write_b16_d16_hi v128, v114 offset:816
	ds_write_b16 v128, v116 offset:2176
	ds_write_b16_d16_hi v128, v116 offset:2448
	ds_write_b16 v128, v118 offset:2720
	ds_write_b16_d16_hi v128, v118 offset:2992
	ds_write_b16 v128, v120 offset:4352
	ds_write_b16_d16_hi v128, v120 offset:4624
	ds_write_b16 v128, v122 offset:4896
	ds_write_b16_d16_hi v128, v122 offset:5168
	ds_write_b16 v128, v124 offset:6528
	ds_write_b16_d16_hi v128, v124 offset:6800
	ds_write_b16 v128, v126 offset:7072
	ds_write_b16_d16_hi v128, v126 offset:7344
	ds_write_b16 v128, v96 offset:64
	ds_write_b16_d16_hi v128, v96 offset:336
	ds_write_b16 v128, v98 offset:608
	ds_write_b16_d16_hi v128, v98 offset:880
	ds_write_b16 v128, v100 offset:2240
	ds_write_b16_d16_hi v128, v100 offset:2512
	ds_write_b16 v128, v102 offset:2784
	ds_write_b16_d16_hi v128, v102 offset:3056
	ds_write_b16 v128, v104 offset:4416
	ds_write_b16_d16_hi v128, v104 offset:4688
	ds_write_b16 v128, v106 offset:4960
	ds_write_b16_d16_hi v128, v106 offset:5232
	ds_write_b16 v128, v108 offset:6592
	ds_write_b16_d16_hi v128, v108 offset:6864
	ds_write_b16 v128, v110 offset:7136
	ds_write_b16_d16_hi v128, v110 offset:7408
	ds_write_b16 v128, v80 offset:8704
	ds_write_b16_d16_hi v128, v80 offset:8976
	ds_write_b16 v128, v82 offset:9248
	ds_write_b16_d16_hi v128, v82 offset:9520
	ds_write_b16 v128, v84 offset:10880
	ds_write_b16_d16_hi v128, v84 offset:11152
	ds_write_b16 v128, v86 offset:11424
	ds_write_b16_d16_hi v128, v86 offset:11696
	ds_write_b16 v128, v88 offset:13056
	ds_write_b16_d16_hi v128, v88 offset:13328
	ds_write_b16 v128, v90 offset:13600
	ds_write_b16_d16_hi v128, v90 offset:13872
	ds_write_b16 v128, v92 offset:15232
	ds_write_b16_d16_hi v128, v92 offset:15504
	ds_write_b16 v128, v94 offset:15776
	ds_write_b16_d16_hi v128, v94 offset:16048
	ds_write_b16 v128, v64 offset:8768
	ds_write_b16_d16_hi v128, v64 offset:9040
	ds_write_b16 v128, v66 offset:9312
	ds_write_b16_d16_hi v128, v66 offset:9584
	ds_write_b16 v128, v68 offset:10944
	ds_write_b16_d16_hi v128, v68 offset:11216
	ds_write_b16 v128, v70 offset:11488
	ds_write_b16_d16_hi v128, v70 offset:11760
	ds_write_b16 v128, v72 offset:13120
	ds_write_b16_d16_hi v128, v72 offset:13392
	ds_write_b16 v128, v74 offset:13664
	ds_write_b16_d16_hi v128, v74 offset:13936
	ds_write_b16 v128, v76 offset:15296
	ds_write_b16_d16_hi v128, v76 offset:15568
	ds_write_b16 v128, v78 offset:15840
	ds_write_b16_d16_hi v128, v78 offset:16112
	s_waitcnt lgkmcnt(0)
	s_barrier
	ds_read_b128 v[132:135], v129
	ds_read_b128 v[136:139], v129 offset:4352
	ds_read_b128 v[140:143], v129 offset:8704
	ds_read_b128 v[144:147], v129 offset:13056
	ds_read_b128 v[148:151], v129 offset:17408
	ds_read_b128 v[152:155], v129 offset:21760
	ds_read_b128 v[156:159], v129 offset:26112
	ds_read_b128 v[160:163], v129 offset:30464
	v_cvt_pk_bf16_f32 v48, v48, v49
	v_cvt_pk_bf16_f32 v50, v50, v51
	v_cvt_pk_bf16_f32 v52, v52, v53
	v_cvt_pk_bf16_f32 v54, v54, v55
	v_cvt_pk_bf16_f32 v56, v56, v57
	v_cvt_pk_bf16_f32 v58, v58, v59
	v_cvt_pk_bf16_f32 v60, v60, v61
	v_cvt_pk_bf16_f32 v62, v62, v63
	v_cvt_pk_bf16_f32 v32, v32, v33
	v_cvt_pk_bf16_f32 v34, v34, v35
	v_cvt_pk_bf16_f32 v36, v36, v37
	v_cvt_pk_bf16_f32 v38, v38, v39
	v_cvt_pk_bf16_f32 v40, v40, v41
	v_cvt_pk_bf16_f32 v42, v42, v43
	v_cvt_pk_bf16_f32 v44, v44, v45
	v_cvt_pk_bf16_f32 v46, v46, v47
	v_cvt_pk_bf16_f32 v16, v16, v17
	v_cvt_pk_bf16_f32 v18, v18, v19
	v_cvt_pk_bf16_f32 v20, v20, v21
	v_cvt_pk_bf16_f32 v22, v22, v23
	v_cvt_pk_bf16_f32 v24, v24, v25
	v_cvt_pk_bf16_f32 v26, v26, v27
	v_cvt_pk_bf16_f32 v28, v28, v29
	v_cvt_pk_bf16_f32 v30, v30, v31
	v_cvt_pk_bf16_f32 v0, v0, v1
	v_cvt_pk_bf16_f32 v2, v2, v3
	v_cvt_pk_bf16_f32 v4, v4, v5
	v_cvt_pk_bf16_f32 v6, v6, v7
	v_cvt_pk_bf16_f32 v8, v8, v9
	v_cvt_pk_bf16_f32 v10, v10, v11
	v_cvt_pk_bf16_f32 v12, v12, v13
	v_cvt_pk_bf16_f32 v14, v14, v15
	s_and_saveexec_b64 s[46:47], s[44:45]
	s_waitcnt lgkmcnt(7)
	global_store_dwordx4 v164, v[132:135], s[42:43]
	s_waitcnt lgkmcnt(6)
	global_store_dwordx4 v165, v[136:139], s[42:43]
	s_waitcnt lgkmcnt(5)
	global_store_dwordx4 v166, v[140:143], s[42:43]
	s_waitcnt lgkmcnt(4)
	global_store_dwordx4 v167, v[144:147], s[42:43]
	s_waitcnt lgkmcnt(3)
	global_store_dwordx4 v168, v[148:151], s[42:43]
	s_waitcnt lgkmcnt(2)
	global_store_dwordx4 v169, v[152:155], s[42:43]
	s_waitcnt lgkmcnt(1)
	global_store_dwordx4 v170, v[156:159], s[42:43]
	s_waitcnt lgkmcnt(0)
	global_store_dwordx4 v171, v[160:163], s[42:43]
	s_or_b64 exec, exec, s[46:47]
	s_barrier
	ds_write_b16 v128, v48
	ds_write_b16_d16_hi v128, v48 offset:272
	ds_write_b16 v128, v50 offset:544
	ds_write_b16_d16_hi v128, v50 offset:816
	ds_write_b16 v128, v52 offset:2176
	ds_write_b16_d16_hi v128, v52 offset:2448
	ds_write_b16 v128, v54 offset:2720
	ds_write_b16_d16_hi v128, v54 offset:2992
	ds_write_b16 v128, v56 offset:4352
	ds_write_b16_d16_hi v128, v56 offset:4624
	ds_write_b16 v128, v58 offset:4896
	ds_write_b16_d16_hi v128, v58 offset:5168
	ds_write_b16 v128, v60 offset:6528
	ds_write_b16_d16_hi v128, v60 offset:6800
	ds_write_b16 v128, v62 offset:7072
	ds_write_b16_d16_hi v128, v62 offset:7344
	ds_write_b16 v128, v32 offset:64
	ds_write_b16_d16_hi v128, v32 offset:336
	ds_write_b16 v128, v34 offset:608
	ds_write_b16_d16_hi v128, v34 offset:880
	ds_write_b16 v128, v36 offset:2240
	ds_write_b16_d16_hi v128, v36 offset:2512
	ds_write_b16 v128, v38 offset:2784
	ds_write_b16_d16_hi v128, v38 offset:3056
	ds_write_b16 v128, v40 offset:4416
	ds_write_b16_d16_hi v128, v40 offset:4688
	ds_write_b16 v128, v42 offset:4960
	ds_write_b16_d16_hi v128, v42 offset:5232
	ds_write_b16 v128, v44 offset:6592
	ds_write_b16_d16_hi v128, v44 offset:6864
	ds_write_b16 v128, v46 offset:7136
	ds_write_b16_d16_hi v128, v46 offset:7408
	ds_write_b16 v128, v16 offset:8704
	ds_write_b16_d16_hi v128, v16 offset:8976
	ds_write_b16 v128, v18 offset:9248
	ds_write_b16_d16_hi v128, v18 offset:9520
	ds_write_b16 v128, v20 offset:10880
	ds_write_b16_d16_hi v128, v20 offset:11152
	ds_write_b16 v128, v22 offset:11424
	ds_write_b16_d16_hi v128, v22 offset:11696
	ds_write_b16 v128, v24 offset:13056
	ds_write_b16_d16_hi v128, v24 offset:13328
	ds_write_b16 v128, v26 offset:13600
	ds_write_b16_d16_hi v128, v26 offset:13872
	ds_write_b16 v128, v28 offset:15232
	ds_write_b16_d16_hi v128, v28 offset:15504
	ds_write_b16 v128, v30 offset:15776
	ds_write_b16_d16_hi v128, v30 offset:16048
	ds_write_b16 v128, v0 offset:8768
	ds_write_b16_d16_hi v128, v0 offset:9040
	ds_write_b16 v128, v2 offset:9312
	ds_write_b16_d16_hi v128, v2 offset:9584
	ds_write_b16 v128, v4 offset:10944
	ds_write_b16_d16_hi v128, v4 offset:11216
	ds_write_b16 v128, v6 offset:11488
	ds_write_b16_d16_hi v128, v6 offset:11760
	ds_write_b16 v128, v8 offset:13120
	ds_write_b16_d16_hi v128, v8 offset:13392
	ds_write_b16 v128, v10 offset:13664
	ds_write_b16_d16_hi v128, v10 offset:13936
	ds_write_b16 v128, v12 offset:15296
	ds_write_b16_d16_hi v128, v12 offset:15568
	ds_write_b16 v128, v14 offset:15840
	ds_write_b16_d16_hi v128, v14 offset:16112
	s_waitcnt lgkmcnt(0)
	s_barrier
	ds_read_b128 v[132:135], v129
	ds_read_b128 v[136:139], v129 offset:4352
	ds_read_b128 v[140:143], v129 offset:8704
	ds_read_b128 v[144:147], v129 offset:13056
	ds_read_b128 v[148:151], v129 offset:17408
	ds_read_b128 v[152:155], v129 offset:21760
	ds_read_b128 v[156:159], v129 offset:26112
	ds_read_b128 v[160:163], v129 offset:30464
	v_add_u32_e32 v164, 0x49000, v164
	v_add_u32_e32 v165, 0x49000, v165
	v_add_u32_e32 v166, 0x49000, v166
	v_add_u32_e32 v167, 0x49000, v167
	v_add_u32_e32 v168, 0x49000, v168
	v_add_u32_e32 v169, 0x49000, v169
	v_add_u32_e32 v170, 0x49000, v170
	v_add_u32_e32 v171, 0x49000, v171
	s_and_saveexec_b64 s[46:47], s[44:45]
	s_waitcnt lgkmcnt(7)
	global_store_dwordx4 v164, v[132:135], s[42:43]
	s_waitcnt lgkmcnt(6)
	global_store_dwordx4 v165, v[136:139], s[42:43]
	s_waitcnt lgkmcnt(5)
	global_store_dwordx4 v166, v[140:143], s[42:43]
	s_waitcnt lgkmcnt(4)
	global_store_dwordx4 v167, v[144:147], s[42:43]
	s_waitcnt lgkmcnt(3)
	global_store_dwordx4 v168, v[148:151], s[42:43]
	s_waitcnt lgkmcnt(2)
	global_store_dwordx4 v169, v[152:155], s[42:43]
	s_waitcnt lgkmcnt(1)
	global_store_dwordx4 v170, v[156:159], s[42:43]
	s_waitcnt lgkmcnt(0)
	global_store_dwordx4 v171, v[160:163], s[42:43]
	s_or_b64 exec, exec, s[46:47]
	s_branch .LBB0_1281

.LBB0_1977:
	ds_read_b128 v[216:219], v188 offset:36864
	ds_read_b128 v[200:203], v187
	ds_read_b128 v[220:223], v188 offset:41472
	ds_read_b128 v[204:207], v187 offset:4608
	ds_read_b128 v[208:211], v187 offset:9216
	ds_read_b128 v[212:215], v176
	s_waitcnt lgkmcnt(4)
	v_mfma_f32_32x32x16_bf16 v[112:127], v[200:203], v[216:219], v[112:127]
	ds_read_b128 v[240:243], v188 offset:36896
	global_load_dwordx4 v[152:155], v190, s[40:41]
	s_waitcnt lgkmcnt(4)
	v_mfma_f32_32x32x16_bf16 v[96:111], v[200:203], v[220:223], v[96:111]
	ds_read_b128 v[224:227], v187 offset:32
	global_load_dwordx4 v[164:167], v191, s[40:41]
	s_waitcnt lgkmcnt(4)
	v_mfma_f32_32x32x16_bf16 v[80:95], v[204:207], v[216:219], v[80:95]
	ds_read_b128 v[244:247], v188 offset:41504
	global_load_dwordx4 v[168:171], v192, s[40:41]
	s_waitcnt lgkmcnt(5)
	v_mfma_f32_32x32x16_bf16 v[64:79], v[204:207], v[220:223], v[64:79]
	ds_read_b128 v[228:231], v187 offset:4640
	global_load_dwordx4 v[172:175], v193, s[40:41]
	s_waitcnt lgkmcnt(5)
	v_mfma_f32_32x32x16_bf16 v[48:63], v[208:211], v[216:219], v[48:63]
	ds_read_b128 v[232:235], v187 offset:9248
	global_load_dwordx4 v[148:151], v196, s[38:39]
	s_waitcnt lgkmcnt(6)
	v_mfma_f32_32x32x16_bf16 v[32:47], v[208:211], v[220:223], v[32:47]
	ds_read_b128 v[236:239], v176 offset:32
	global_load_dwordx4 v[156:159], v197, s[38:39]
	s_add_u32 s38, s38, 0x80
	s_addc_u32 s39, s39, 0
	s_add_u32 s40, s40, 0x80
	s_addc_u32 s41, s41, 0
	s_add_u32 s12, s12, 0x80
	s_waitcnt lgkmcnt(6)
	v_mfma_f32_32x32x16_bf16 v[16:31], v[212:215], v[216:219], v[16:31]
	s_waitcnt lgkmcnt(6)
	v_mfma_f32_32x32x16_bf16 v[0:15], v[212:215], v[220:223], v[0:15]
	s_waitcnt lgkmcnt(4)
	v_mfma_f32_32x32x16_bf16 v[112:127], v[224:227], v[240:243], v[112:127]
	ds_read_b128 v[200:203], v187 offset:64
	s_waitcnt lgkmcnt(4)
	v_mfma_f32_32x32x16_bf16 v[96:111], v[224:227], v[244:247], v[96:111]
	ds_read_b128 v[204:207], v187 offset:4672
	s_waitcnt lgkmcnt(4)
	v_mfma_f32_32x32x16_bf16 v[80:95], v[228:231], v[240:243], v[80:95]
	ds_read_b128 v[208:211], v187 offset:9280
	s_waitcnt lgkmcnt(5)
	v_mfma_f32_32x32x16_bf16 v[64:79], v[228:231], v[244:247], v[64:79]
	ds_read_b128 v[212:215], v176 offset:64
	s_waitcnt lgkmcnt(5)
	v_mfma_f32_32x32x16_bf16 v[48:63], v[232:235], v[240:243], v[48:63]
	ds_read_b128 v[216:219], v188 offset:36928
	s_waitcnt lgkmcnt(6)
	v_mfma_f32_32x32x16_bf16 v[32:47], v[232:235], v[244:247], v[32:47]
	ds_read_b128 v[220:223], v188 offset:41536
	s_waitcnt lgkmcnt(6)
	v_mfma_f32_32x32x16_bf16 v[16:31], v[236:239], v[240:243], v[16:31]
	s_waitcnt lgkmcnt(6)
	v_mfma_f32_32x32x16_bf16 v[0:15], v[236:239], v[244:247], v[0:15]
	s_waitcnt lgkmcnt(1)
	v_mfma_f32_32x32x16_bf16 v[112:127], v[200:203], v[216:219], v[112:127]
	ds_read_b128 v[224:227], v187 offset:96
	s_waitcnt lgkmcnt(1)
	v_mfma_f32_32x32x16_bf16 v[96:111], v[200:203], v[220:223], v[96:111]
	ds_read_b128 v[228:231], v187 offset:4704
	s_waitcnt lgkmcnt(3)
	v_mfma_f32_32x32x16_bf16 v[80:95], v[204:207], v[216:219], v[80:95]
	ds_read_b128 v[232:235], v187 offset:9312
	s_waitcnt lgkmcnt(3)
	v_mfma_f32_32x32x16_bf16 v[64:79], v[204:207], v[220:223], v[64:79]
	ds_read_b128 v[236:239], v176 offset:96
	s_waitcnt lgkmcnt(5)
	v_mfma_f32_32x32x16_bf16 v[48:63], v[208:211], v[216:219], v[48:63]
	ds_read_b128 v[240:243], v188 offset:36960
	s_waitcnt lgkmcnt(5)
	v_mfma_f32_32x32x16_bf16 v[32:47], v[208:211], v[220:223], v[32:47]
	ds_read_b128 v[244:247], v188 offset:41568
	s_waitcnt lgkmcnt(7)
	v_mfma_f32_32x32x16_bf16 v[16:31], v[212:215], v[216:219], v[16:31]
	s_waitcnt lgkmcnt(6)
	v_mfma_f32_32x32x16_bf16 v[0:15], v[212:215], v[220:223], v[0:15]
	s_waitcnt lgkmcnt(0)
	s_barrier
	s_waitcnt vmcnt(6)
	s_waitcnt lgkmcnt(1)
	v_mfma_f32_32x32x16_bf16 v[112:127], v[224:227], v[240:243], v[112:127]
	ds_write_b128 v189, v[160:163]
	ds_write_b128 v189, v[128:131] offset:4608
	s_waitcnt lgkmcnt(2)
	v_mfma_f32_32x32x16_bf16 v[96:111], v[224:227], v[244:247], v[96:111]
	ds_write_b128 v189, v[132:135] offset:9216
	global_load_dwordx4 v[160:163], v190, s[38:39]
	s_waitcnt lgkmcnt(4)
	v_mfma_f32_32x32x16_bf16 v[80:95], v[228:231], v[240:243], v[80:95]
	ds_write_b128 v189, v[136:139] offset:13824
	ds_write_b128 v189, v[140:143] offset:18432
	global_load_dwordx4 v[128:131], v191, s[38:39]
	s_waitcnt lgkmcnt(5)
	v_mfma_f32_32x32x16_bf16 v[64:79], v[228:231], v[244:247], v[64:79]
	ds_write_b128 v189, v[144:147] offset:23040
	global_load_dwordx4 v[132:135], v192, s[38:39]
	s_waitcnt lgkmcnt(7)
	v_mfma_f32_32x32x16_bf16 v[48:63], v[232:235], v[240:243], v[48:63]
	s_waitcnt vmcnt(3)
	ds_write_b128 v189, v[148:151] offset:27648
	ds_write_b128 v189, v[156:159] offset:32256
	global_load_dwordx4 v[136:139], v193, s[38:39]
	s_waitcnt lgkmcnt(8)
	v_mfma_f32_32x32x16_bf16 v[32:47], v[232:235], v[244:247], v[32:47]
	ds_write_b128 v189, v[152:155] offset:36864
	global_load_dwordx4 v[140:143], v194, s[38:39]
	s_waitcnt lgkmcnt(10)
	v_mfma_f32_32x32x16_bf16 v[16:31], v[236:239], v[240:243], v[16:31]
	ds_write_b128 v189, v[164:167] offset:41472
	ds_write_b128 v189, v[168:171] offset:46080
	global_load_dwordx4 v[144:147], v195, s[38:39]
	s_waitcnt lgkmcnt(11)
	v_mfma_f32_32x32x16_bf16 v[0:15], v[236:239], v[244:247], v[0:15]
	ds_write_b128 v189, v[172:175] offset:50688
	s_waitcnt lgkmcnt(0)
	s_barrier
	s_cmpk_lg_i32 s12, 0x780
	s_cbranch_scc1 .LBB0_1977
	ds_read_b128 v[216:219], v188 offset:36864
	ds_read_b128 v[200:203], v187
	ds_read_b128 v[220:223], v188 offset:41472
	ds_read_b128 v[204:207], v187 offset:4608
	ds_read_b128 v[208:211], v187 offset:9216
	ds_read_b128 v[212:215], v176
	s_waitcnt lgkmcnt(4)
	v_mfma_f32_32x32x16_bf16 v[112:127], v[200:203], v[216:219], v[112:127]
	ds_read_b128 v[240:243], v188 offset:36896
	s_waitcnt lgkmcnt(4)
	v_mfma_f32_32x32x16_bf16 v[96:111], v[200:203], v[220:223], v[96:111]
	ds_read_b128 v[224:227], v187 offset:32
	s_waitcnt lgkmcnt(4)
	v_mfma_f32_32x32x16_bf16 v[80:95], v[204:207], v[216:219], v[80:95]
	ds_read_b128 v[244:247], v188 offset:41504
	s_waitcnt lgkmcnt(5)
	v_mfma_f32_32x32x16_bf16 v[64:79], v[204:207], v[220:223], v[64:79]
	ds_read_b128 v[228:231], v187 offset:4640
	s_waitcnt lgkmcnt(5)
	v_mfma_f32_32x32x16_bf16 v[48:63], v[208:211], v[216:219], v[48:63]
	ds_read_b128 v[232:235], v187 offset:9248
	s_waitcnt lgkmcnt(6)
	v_mfma_f32_32x32x16_bf16 v[32:47], v[208:211], v[220:223], v[32:47]
	ds_read_b128 v[236:239], v176 offset:32
	s_waitcnt lgkmcnt(6)
	v_mfma_f32_32x32x16_bf16 v[16:31], v[212:215], v[216:219], v[16:31]
	s_waitcnt lgkmcnt(6)
	v_mfma_f32_32x32x16_bf16 v[0:15], v[212:215], v[220:223], v[0:15]
	s_waitcnt lgkmcnt(4)
	v_mfma_f32_32x32x16_bf16 v[112:127], v[224:227], v[240:243], v[112:127]
	ds_read_b128 v[200:203], v187 offset:64
	s_waitcnt lgkmcnt(4)
	v_mfma_f32_32x32x16_bf16 v[96:111], v[224:227], v[244:247], v[96:111]
	ds_read_b128 v[204:207], v187 offset:4672
	s_waitcnt lgkmcnt(4)
	v_mfma_f32_32x32x16_bf16 v[80:95], v[228:231], v[240:243], v[80:95]
	ds_read_b128 v[208:211], v187 offset:9280
	s_waitcnt lgkmcnt(5)
	v_mfma_f32_32x32x16_bf16 v[64:79], v[228:231], v[244:247], v[64:79]
	ds_read_b128 v[212:215], v176 offset:64
	s_waitcnt lgkmcnt(5)
	v_mfma_f32_32x32x16_bf16 v[48:63], v[232:235], v[240:243], v[48:63]
	ds_read_b128 v[216:219], v188 offset:36928
	s_waitcnt lgkmcnt(6)
	v_mfma_f32_32x32x16_bf16 v[32:47], v[232:235], v[244:247], v[32:47]
	ds_read_b128 v[220:223], v188 offset:41536
	s_waitcnt lgkmcnt(6)
	v_mfma_f32_32x32x16_bf16 v[16:31], v[236:239], v[240:243], v[16:31]
	s_waitcnt lgkmcnt(6)
	v_mfma_f32_32x32x16_bf16 v[0:15], v[236:239], v[244:247], v[0:15]
	s_waitcnt lgkmcnt(1)
	v_mfma_f32_32x32x16_bf16 v[112:127], v[200:203], v[216:219], v[112:127]
	ds_read_b128 v[224:227], v187 offset:96
	s_waitcnt lgkmcnt(1)
	v_mfma_f32_32x32x16_bf16 v[96:111], v[200:203], v[220:223], v[96:111]
	ds_read_b128 v[228:231], v187 offset:4704
	s_waitcnt lgkmcnt(3)
	v_mfma_f32_32x32x16_bf16 v[80:95], v[204:207], v[216:219], v[80:95]
	ds_read_b128 v[232:235], v187 offset:9312
	s_waitcnt lgkmcnt(3)
	v_mfma_f32_32x32x16_bf16 v[64:79], v[204:207], v[220:223], v[64:79]
	ds_read_b128 v[236:239], v176 offset:96
	s_waitcnt lgkmcnt(5)
	v_mfma_f32_32x32x16_bf16 v[48:63], v[208:211], v[216:219], v[48:63]
	ds_read_b128 v[240:243], v188 offset:36960
	s_waitcnt lgkmcnt(5)
	v_mfma_f32_32x32x16_bf16 v[32:47], v[208:211], v[220:223], v[32:47]
	ds_read_b128 v[244:247], v188 offset:41568
	s_waitcnt lgkmcnt(7)
	v_mfma_f32_32x32x16_bf16 v[16:31], v[212:215], v[216:219], v[16:31]
	s_waitcnt lgkmcnt(6)
	v_mfma_f32_32x32x16_bf16 v[0:15], v[212:215], v[220:223], v[0:15]
	s_waitcnt lgkmcnt(1)
	v_mfma_f32_32x32x16_bf16 v[112:127], v[224:227], v[240:243], v[112:127]
	s_waitcnt lgkmcnt(0)
	v_mfma_f32_32x32x16_bf16 v[96:111], v[224:227], v[244:247], v[96:111]
	s_waitcnt lgkmcnt(1)
	v_mfma_f32_32x32x16_bf16 v[80:95], v[228:231], v[240:243], v[80:95]
	s_waitcnt lgkmcnt(0)
	v_mfma_f32_32x32x16_bf16 v[64:79], v[228:231], v[244:247], v[64:79]
	s_waitcnt lgkmcnt(1)
	v_mfma_f32_32x32x16_bf16 v[48:63], v[232:235], v[240:243], v[48:63]
	s_waitcnt lgkmcnt(0)
	v_mfma_f32_32x32x16_bf16 v[32:47], v[232:235], v[244:247], v[32:47]
	s_waitcnt lgkmcnt(1)
	v_mfma_f32_32x32x16_bf16 v[16:31], v[236:239], v[240:243], v[16:31]
	s_waitcnt lgkmcnt(0)
	v_mfma_f32_32x32x16_bf16 v[0:15], v[236:239], v[244:247], v[0:15]
	s_waitcnt vmcnt(0)
	s_mul_i32 s42, s6, 0x2000
	s_add_u32 s44, s30, s42
	s_addc_u32 s45, s31, 0
	s_lshl_b32 s42, s58, 1
	s_add_u32 s44, s44, s42
	s_addc_u32 s45, s45, 0
	s_add_u32 s44, s44, 0x7157900
	s_addc_u32 s45, s45, 0
	s_mov_b32 s43, 1
	v_max_f32_e32 v112, 0, v112
	v_max_f32_e32 v113, 0, v113
	v_mul_f32_e32 v112, v112, v112
	v_mul_f32_e32 v113, v113, v113
	v_cvt_pk_bf16_f32 v190, v112, v113
	v_max_f32_e32 v114, 0, v114
	v_max_f32_e32 v115, 0, v115
	v_mul_f32_e32 v114, v114, v114
	v_mul_f32_e32 v115, v115, v115
	v_cvt_pk_bf16_f32 v191, v114, v115
	v_max_f32_e32 v116, 0, v116
	v_max_f32_e32 v117, 0, v117
	v_mul_f32_e32 v116, v116, v116
	v_mul_f32_e32 v117, v117, v117
	v_cvt_pk_bf16_f32 v192, v116, v117
	v_max_f32_e32 v118, 0, v118
	v_max_f32_e32 v119, 0, v119
	v_mul_f32_e32 v118, v118, v118
	v_mul_f32_e32 v119, v119, v119
	v_cvt_pk_bf16_f32 v193, v118, v119
	v_max_f32_e32 v120, 0, v120
	v_max_f32_e32 v121, 0, v121
	v_mul_f32_e32 v120, v120, v120
	v_mul_f32_e32 v121, v121, v121
	v_cvt_pk_bf16_f32 v194, v120, v121
	v_max_f32_e32 v122, 0, v122
	v_max_f32_e32 v123, 0, v123
	v_mul_f32_e32 v122, v122, v122
	v_mul_f32_e32 v123, v123, v123
	v_cvt_pk_bf16_f32 v195, v122, v123
	v_max_f32_e32 v124, 0, v124
	v_max_f32_e32 v125, 0, v125
	v_mul_f32_e32 v124, v124, v124
	v_mul_f32_e32 v125, v125, v125
	v_cvt_pk_bf16_f32 v196, v124, v125
	v_max_f32_e32 v126, 0, v126
	v_max_f32_e32 v127, 0, v127
	v_mul_f32_e32 v126, v126, v126
	v_mul_f32_e32 v127, v127, v127
	v_cvt_pk_bf16_f32 v197, v126, v127
	v_max_f32_e32 v96, 0, v96
	v_max_f32_e32 v97, 0, v97
	v_mul_f32_e32 v96, v96, v96
	v_mul_f32_e32 v97, v97, v97
	v_cvt_pk_bf16_f32 v198, v96, v97
	v_max_f32_e32 v98, 0, v98
	v_max_f32_e32 v99, 0, v99
	v_mul_f32_e32 v98, v98, v98
	v_mul_f32_e32 v99, v99, v99
	v_cvt_pk_bf16_f32 v199, v98, v99
	v_max_f32_e32 v100, 0, v100
	v_max_f32_e32 v101, 0, v101
	v_mul_f32_e32 v100, v100, v100
	v_mul_f32_e32 v101, v101, v101
	v_cvt_pk_bf16_f32 v200, v100, v101
	v_max_f32_e32 v102, 0, v102
	v_max_f32_e32 v103, 0, v103
	v_mul_f32_e32 v102, v102, v102
	v_mul_f32_e32 v103, v103, v103
	v_cvt_pk_bf16_f32 v201, v102, v103
	v_max_f32_e32 v104, 0, v104
	v_max_f32_e32 v105, 0, v105
	v_mul_f32_e32 v104, v104, v104
	v_mul_f32_e32 v105, v105, v105
	v_cvt_pk_bf16_f32 v202, v104, v105
	v_max_f32_e32 v106, 0, v106
	v_max_f32_e32 v107, 0, v107
	v_mul_f32_e32 v106, v106, v106
	v_mul_f32_e32 v107, v107, v107
	v_cvt_pk_bf16_f32 v203, v106, v107
	v_max_f32_e32 v108, 0, v108
	v_max_f32_e32 v109, 0, v109
	v_mul_f32_e32 v108, v108, v108
	v_mul_f32_e32 v109, v109, v109
	v_cvt_pk_bf16_f32 v204, v108, v109
	v_max_f32_e32 v110, 0, v110
	v_max_f32_e32 v111, 0, v111
	v_mul_f32_e32 v110, v110, v110
	v_mul_f32_e32 v111, v111, v111
	v_cvt_pk_bf16_f32 v205, v110, v111
	v_max_f32_e32 v80, 0, v80
	v_max_f32_e32 v81, 0, v81
	v_mul_f32_e32 v80, v80, v80
	v_mul_f32_e32 v81, v81, v81
	v_cvt_pk_bf16_f32 v206, v80, v81
	v_max_f32_e32 v82, 0, v82
	v_max_f32_e32 v83, 0, v83
	v_mul_f32_e32 v82, v82, v82
	v_mul_f32_e32 v83, v83, v83
	v_cvt_pk_bf16_f32 v207, v82, v83
	v_max_f32_e32 v84, 0, v84
	v_max_f32_e32 v85, 0, v85
	v_mul_f32_e32 v84, v84, v84
	v_mul_f32_e32 v85, v85, v85
	v_cvt_pk_bf16_f32 v208, v84, v85
	v_max_f32_e32 v86, 0, v86
	v_max_f32_e32 v87, 0, v87
	v_mul_f32_e32 v86, v86, v86
	v_mul_f32_e32 v87, v87, v87
	v_cvt_pk_bf16_f32 v209, v86, v87
	v_max_f32_e32 v88, 0, v88
	v_max_f32_e32 v89, 0, v89
	v_mul_f32_e32 v88, v88, v88
	v_mul_f32_e32 v89, v89, v89
	v_cvt_pk_bf16_f32 v210, v88, v89
	v_max_f32_e32 v90, 0, v90
	v_max_f32_e32 v91, 0, v91
	v_mul_f32_e32 v90, v90, v90
	v_mul_f32_e32 v91, v91, v91
	v_cvt_pk_bf16_f32 v211, v90, v91
	v_max_f32_e32 v92, 0, v92
	v_max_f32_e32 v93, 0, v93
	v_mul_f32_e32 v92, v92, v92
	v_mul_f32_e32 v93, v93, v93
	v_cvt_pk_bf16_f32 v212, v92, v93
	v_max_f32_e32 v94, 0, v94
	v_max_f32_e32 v95, 0, v95
	v_mul_f32_e32 v94, v94, v94
	v_mul_f32_e32 v95, v95, v95
	v_cvt_pk_bf16_f32 v213, v94, v95
	v_max_f32_e32 v64, 0, v64
	v_max_f32_e32 v65, 0, v65
	v_mul_f32_e32 v64, v64, v64
	v_mul_f32_e32 v65, v65, v65
	v_cvt_pk_bf16_f32 v214, v64, v65
	v_max_f32_e32 v66, 0, v66
	v_max_f32_e32 v67, 0, v67
	v_mul_f32_e32 v66, v66, v66
	v_mul_f32_e32 v67, v67, v67
	v_cvt_pk_bf16_f32 v215, v66, v67
	v_max_f32_e32 v68, 0, v68
	v_max_f32_e32 v69, 0, v69
	v_mul_f32_e32 v68, v68, v68
	v_mul_f32_e32 v69, v69, v69
	v_cvt_pk_bf16_f32 v216, v68, v69
	v_max_f32_e32 v70, 0, v70
	v_max_f32_e32 v71, 0, v71
	v_mul_f32_e32 v70, v70, v70
	v_mul_f32_e32 v71, v71, v71
	v_cvt_pk_bf16_f32 v217, v70, v71
	v_max_f32_e32 v72, 0, v72
	v_max_f32_e32 v73, 0, v73
	v_mul_f32_e32 v72, v72, v72
	v_mul_f32_e32 v73, v73, v73
	v_cvt_pk_bf16_f32 v218, v72, v73
	v_max_f32_e32 v74, 0, v74
	v_max_f32_e32 v75, 0, v75
	v_mul_f32_e32 v74, v74, v74
	v_mul_f32_e32 v75, v75, v75
	v_cvt_pk_bf16_f32 v219, v74, v75
	v_max_f32_e32 v76, 0, v76
	v_max_f32_e32 v77, 0, v77
	v_mul_f32_e32 v76, v76, v76
	v_mul_f32_e32 v77, v77, v77
	v_cvt_pk_bf16_f32 v220, v76, v77
	v_max_f32_e32 v78, 0, v78
	v_max_f32_e32 v79, 0, v79
	v_mul_f32_e32 v78, v78, v78
	v_mul_f32_e32 v79, v79, v79
	v_cvt_pk_bf16_f32 v221, v78, v79
	v_max_f32_e32 v48, 0, v48
	v_max_f32_e32 v49, 0, v49
	v_mul_f32_e32 v48, v48, v48
	v_mul_f32_e32 v49, v49, v49
	v_cvt_pk_bf16_f32 v222, v48, v49
	v_max_f32_e32 v50, 0, v50
	v_max_f32_e32 v51, 0, v51
	v_mul_f32_e32 v50, v50, v50
	v_mul_f32_e32 v51, v51, v51
	v_cvt_pk_bf16_f32 v223, v50, v51
	v_max_f32_e32 v52, 0, v52
	v_max_f32_e32 v53, 0, v53
	v_mul_f32_e32 v52, v52, v52
	v_mul_f32_e32 v53, v53, v53
	v_cvt_pk_bf16_f32 v224, v52, v53
	v_max_f32_e32 v54, 0, v54
	v_max_f32_e32 v55, 0, v55
	v_mul_f32_e32 v54, v54, v54
	v_mul_f32_e32 v55, v55, v55
	v_cvt_pk_bf16_f32 v225, v54, v55
	v_max_f32_e32 v56, 0, v56
	v_max_f32_e32 v57, 0, v57
	v_mul_f32_e32 v56, v56, v56
	v_mul_f32_e32 v57, v57, v57
	v_cvt_pk_bf16_f32 v226, v56, v57
	v_max_f32_e32 v58, 0, v58
	v_max_f32_e32 v59, 0, v59
	v_mul_f32_e32 v58, v58, v58
	v_mul_f32_e32 v59, v59, v59
	v_cvt_pk_bf16_f32 v227, v58, v59
	v_max_f32_e32 v60, 0, v60
	v_max_f32_e32 v61, 0, v61
	v_mul_f32_e32 v60, v60, v60
	v_mul_f32_e32 v61, v61, v61
	v_cvt_pk_bf16_f32 v228, v60, v61
	v_max_f32_e32 v62, 0, v62
	v_max_f32_e32 v63, 0, v63
	v_mul_f32_e32 v62, v62, v62
	v_mul_f32_e32 v63, v63, v63
	v_cvt_pk_bf16_f32 v229, v62, v63
	v_max_f32_e32 v32, 0, v32
	v_max_f32_e32 v33, 0, v33
	v_mul_f32_e32 v32, v32, v32
	v_mul_f32_e32 v33, v33, v33
	v_cvt_pk_bf16_f32 v230, v32, v33
	v_max_f32_e32 v34, 0, v34
	v_max_f32_e32 v35, 0, v35
	v_mul_f32_e32 v34, v34, v34
	v_mul_f32_e32 v35, v35, v35
	v_cvt_pk_bf16_f32 v231, v34, v35
	v_max_f32_e32 v36, 0, v36
	v_max_f32_e32 v37, 0, v37
	v_mul_f32_e32 v36, v36, v36
	v_mul_f32_e32 v37, v37, v37
	v_cvt_pk_bf16_f32 v232, v36, v37
	v_max_f32_e32 v38, 0, v38
	v_max_f32_e32 v39, 0, v39
	v_mul_f32_e32 v38, v38, v38
	v_mul_f32_e32 v39, v39, v39
	v_cvt_pk_bf16_f32 v233, v38, v39
	v_max_f32_e32 v40, 0, v40
	v_max_f32_e32 v41, 0, v41
	v_mul_f32_e32 v40, v40, v40
	v_mul_f32_e32 v41, v41, v41
	v_cvt_pk_bf16_f32 v234, v40, v41
	v_max_f32_e32 v42, 0, v42
	v_max_f32_e32 v43, 0, v43
	v_mul_f32_e32 v42, v42, v42
	v_mul_f32_e32 v43, v43, v43
	v_cvt_pk_bf16_f32 v235, v42, v43
	v_max_f32_e32 v44, 0, v44
	v_max_f32_e32 v45, 0, v45
	v_mul_f32_e32 v44, v44, v44
	v_mul_f32_e32 v45, v45, v45
	v_cvt_pk_bf16_f32 v236, v44, v45
	v_max_f32_e32 v46, 0, v46
	v_max_f32_e32 v47, 0, v47
	v_mul_f32_e32 v46, v46, v46
	v_mul_f32_e32 v47, v47, v47
	v_cvt_pk_bf16_f32 v237, v46, v47
	v_max_f32_e32 v16, 0, v16
	v_max_f32_e32 v17, 0, v17
	v_mul_f32_e32 v16, v16, v16
	v_mul_f32_e32 v17, v17, v17
	v_cvt_pk_bf16_f32 v238, v16, v17
	v_max_f32_e32 v18, 0, v18
	v_max_f32_e32 v19, 0, v19
	v_mul_f32_e32 v18, v18, v18
	v_mul_f32_e32 v19, v19, v19
	v_cvt_pk_bf16_f32 v239, v18, v19
	v_max_f32_e32 v20, 0, v20
	v_max_f32_e32 v21, 0, v21
	v_mul_f32_e32 v20, v20, v20
	v_mul_f32_e32 v21, v21, v21
	v_cvt_pk_bf16_f32 v240, v20, v21
	v_max_f32_e32 v22, 0, v22
	v_max_f32_e32 v23, 0, v23
	v_mul_f32_e32 v22, v22, v22
	v_mul_f32_e32 v23, v23, v23
	v_cvt_pk_bf16_f32 v241, v22, v23
	v_max_f32_e32 v24, 0, v24
	v_max_f32_e32 v25, 0, v25
	v_mul_f32_e32 v24, v24, v24
	v_mul_f32_e32 v25, v25, v25
	v_cvt_pk_bf16_f32 v242, v24, v25
	v_max_f32_e32 v26, 0, v26
	v_max_f32_e32 v27, 0, v27
	v_mul_f32_e32 v26, v26, v26
	v_mul_f32_e32 v27, v27, v27
	v_cvt_pk_bf16_f32 v243, v26, v27
	v_max_f32_e32 v28, 0, v28
	v_max_f32_e32 v29, 0, v29
	v_mul_f32_e32 v28, v28, v28
	v_mul_f32_e32 v29, v29, v29
	v_cvt_pk_bf16_f32 v244, v28, v29
	v_max_f32_e32 v30, 0, v30
	v_max_f32_e32 v31, 0, v31
	v_mul_f32_e32 v30, v30, v30
	v_mul_f32_e32 v31, v31, v31
	v_cvt_pk_bf16_f32 v245, v30, v31
	v_max_f32_e32 v0, 0, v0
	v_max_f32_e32 v1, 0, v1
	v_mul_f32_e32 v0, v0, v0
	v_mul_f32_e32 v1, v1, v1
	v_cvt_pk_bf16_f32 v246, v0, v1
	v_max_f32_e32 v2, 0, v2
	v_max_f32_e32 v3, 0, v3
	v_mul_f32_e32 v2, v2, v2
	v_mul_f32_e32 v3, v3, v3
	v_cvt_pk_bf16_f32 v247, v2, v3
	v_max_f32_e32 v4, 0, v4
	v_max_f32_e32 v5, 0, v5
	v_mul_f32_e32 v4, v4, v4
	v_mul_f32_e32 v5, v5, v5
	v_cvt_pk_bf16_f32 v248, v4, v5
	v_max_f32_e32 v6, 0, v6
	v_max_f32_e32 v7, 0, v7
	v_mul_f32_e32 v6, v6, v6
	v_mul_f32_e32 v7, v7, v7
	v_cvt_pk_bf16_f32 v249, v6, v7
	v_max_f32_e32 v8, 0, v8
	v_max_f32_e32 v9, 0, v9
	v_mul_f32_e32 v8, v8, v8
	v_mul_f32_e32 v9, v9, v9
	v_cvt_pk_bf16_f32 v250, v8, v9
	v_max_f32_e32 v10, 0, v10
	v_max_f32_e32 v11, 0, v11
	v_mul_f32_e32 v10, v10, v10
	v_mul_f32_e32 v11, v11, v11
	v_cvt_pk_bf16_f32 v251, v10, v11
	v_max_f32_e32 v12, 0, v12
	v_max_f32_e32 v13, 0, v13
	v_mul_f32_e32 v12, v12, v12
	v_mul_f32_e32 v13, v13, v13
	v_cvt_pk_bf16_f32 v252, v12, v13
	v_max_f32_e32 v14, 0, v14
	v_max_f32_e32 v15, 0, v15
	v_mul_f32_e32 v14, v14, v14
	v_mul_f32_e32 v15, v15, v15
	v_cvt_pk_bf16_f32 v253, v14, v15
	s_add_i32 s57, s57, s21
	s_add_i32 s56, s56, s21
	s_cmpk_lt_u32 s57, 0x200
	s_cbranch_scc1 .LBB0_1976
	v_and_b32_e32 v3, 15, v182
	v_lshrrev_b32_e32 v4, 4, v182
	v_mul_u32_u24_e32 v2, 0x2000, v4
	v_lshl_add_u32 v2, v3, 4, v2
	v_mul_u32_u24_e32 v1, 0x110, v4
	v_lshl_add_u32 v1, v3, 4, v1
	v_lshrrev_b32_e32 v3, 7, v182
	v_bfe_u32 v4, v182, 5, 1
	v_lshlrev_b32_e32 v3, 6, v3
	v_lshl_or_b32 v3, v4, 2, v3
	v_mul_u32_u24_e32 v3, 136, v3
	v_and_b32_e32 v4, 0x5f, v182
	v_add_lshl_u32 v0, v3, v4, 1
	s_barrier
	ds_write_b16 v0, v190
	ds_write_b16_d16_hi v0, v190 offset:272
	ds_write_b16 v0, v191 offset:544
	ds_write_b16_d16_hi v0, v191 offset:816
	ds_write_b16 v0, v192 offset:2176
	ds_write_b16_d16_hi v0, v192 offset:2448
	ds_write_b16 v0, v193 offset:2720
	ds_write_b16_d16_hi v0, v193 offset:2992
	ds_write_b16 v0, v194 offset:4352
	ds_write_b16_d16_hi v0, v194 offset:4624
	ds_write_b16 v0, v195 offset:4896
	ds_write_b16_d16_hi v0, v195 offset:5168
	ds_write_b16 v0, v196 offset:6528
	ds_write_b16_d16_hi v0, v196 offset:6800
	ds_write_b16 v0, v197 offset:7072
	ds_write_b16_d16_hi v0, v197 offset:7344
	ds_write_b16 v0, v198 offset:64
	ds_write_b16_d16_hi v0, v198 offset:336
	ds_write_b16 v0, v199 offset:608
	ds_write_b16_d16_hi v0, v199 offset:880
	ds_write_b16 v0, v200 offset:2240
	ds_write_b16_d16_hi v0, v200 offset:2512
	ds_write_b16 v0, v201 offset:2784
	ds_write_b16_d16_hi v0, v201 offset:3056
	ds_write_b16 v0, v202 offset:4416
	ds_write_b16_d16_hi v0, v202 offset:4688
	ds_write_b16 v0, v203 offset:4960
	ds_write_b16_d16_hi v0, v203 offset:5232
	ds_write_b16 v0, v204 offset:6592
	ds_write_b16_d16_hi v0, v204 offset:6864
	ds_write_b16 v0, v205 offset:7136
	ds_write_b16_d16_hi v0, v205 offset:7408
	ds_write_b16 v0, v206 offset:8704
	ds_write_b16_d16_hi v0, v206 offset:8976
	ds_write_b16 v0, v207 offset:9248
	ds_write_b16_d16_hi v0, v207 offset:9520
	ds_write_b16 v0, v208 offset:10880
	ds_write_b16_d16_hi v0, v208 offset:11152
	ds_write_b16 v0, v209 offset:11424
	ds_write_b16_d16_hi v0, v209 offset:11696
	ds_write_b16 v0, v210 offset:13056
	ds_write_b16_d16_hi v0, v210 offset:13328
	ds_write_b16 v0, v211 offset:13600
	ds_write_b16_d16_hi v0, v211 offset:13872
	ds_write_b16 v0, v212 offset:15232
	ds_write_b16_d16_hi v0, v212 offset:15504
	ds_write_b16 v0, v213 offset:15776
	ds_write_b16_d16_hi v0, v213 offset:16048
	ds_write_b16 v0, v214 offset:8768
	ds_write_b16_d16_hi v0, v214 offset:9040
	ds_write_b16 v0, v215 offset:9312
	ds_write_b16_d16_hi v0, v215 offset:9584
	ds_write_b16 v0, v216 offset:10944
	ds_write_b16_d16_hi v0, v216 offset:11216
	ds_write_b16 v0, v217 offset:11488
	ds_write_b16_d16_hi v0, v217 offset:11760
	ds_write_b16 v0, v218 offset:13120
	ds_write_b16_d16_hi v0, v218 offset:13392
	ds_write_b16 v0, v219 offset:13664
	ds_write_b16_d16_hi v0, v219 offset:13936
	ds_write_b16 v0, v220 offset:15296
	ds_write_b16_d16_hi v0, v220 offset:15568
	ds_write_b16 v0, v221 offset:15840
	ds_write_b16_d16_hi v0, v221 offset:16112
	s_waitcnt lgkmcnt(0)
	s_barrier
	ds_read_b128 v[8:11], v1
	ds_read_b128 v[12:15], v1 offset:4352
	ds_read_b128 v[16:19], v1 offset:8704
	ds_read_b128 v[20:23], v1 offset:13056
	ds_read_b128 v[24:27], v1 offset:17408
	ds_read_b128 v[28:31], v1 offset:21760
	ds_read_b128 v[32:35], v1 offset:26112
	ds_read_b128 v[36:39], v1 offset:30464
	s_add_u32 s38, s44, 0x0
	s_addc_u32 s39, s45, 0
	s_waitcnt lgkmcnt(7)
	global_store_dwordx4 v2, v[8:11], s[38:39]
	s_add_u32 s38, s44, 0x20000
	s_addc_u32 s39, s45, 0
	s_waitcnt lgkmcnt(6)
	global_store_dwordx4 v2, v[12:15], s[38:39]
	s_add_u32 s38, s44, 0x40000
	s_addc_u32 s39, s45, 0
	s_waitcnt lgkmcnt(5)
	global_store_dwordx4 v2, v[16:19], s[38:39]
	s_add_u32 s38, s44, 0x60000
	s_addc_u32 s39, s45, 0
	s_waitcnt lgkmcnt(4)
	global_store_dwordx4 v2, v[20:23], s[38:39]
	s_add_u32 s38, s44, 0x100000
	s_addc_u32 s39, s45, 0
	s_waitcnt lgkmcnt(3)
	global_store_dwordx4 v2, v[24:27], s[38:39]
	s_add_u32 s38, s44, 0x120000
	s_addc_u32 s39, s45, 0
	s_waitcnt lgkmcnt(2)
	global_store_dwordx4 v2, v[28:31], s[38:39]
	s_add_u32 s38, s44, 0x140000
	s_addc_u32 s39, s45, 0
	s_waitcnt lgkmcnt(1)
	global_store_dwordx4 v2, v[32:35], s[38:39]
	s_add_u32 s38, s44, 0x160000
	s_addc_u32 s39, s45, 0
	s_waitcnt lgkmcnt(0)
	global_store_dwordx4 v2, v[36:39], s[38:39]
	s_barrier
	ds_write_b16 v0, v222
	ds_write_b16_d16_hi v0, v222 offset:272
	ds_write_b16 v0, v223 offset:544
	ds_write_b16_d16_hi v0, v223 offset:816
	ds_write_b16 v0, v224 offset:2176
	ds_write_b16_d16_hi v0, v224 offset:2448
	ds_write_b16 v0, v225 offset:2720
	ds_write_b16_d16_hi v0, v225 offset:2992
	ds_write_b16 v0, v226 offset:4352
	ds_write_b16_d16_hi v0, v226 offset:4624
	ds_write_b16 v0, v227 offset:4896
	ds_write_b16_d16_hi v0, v227 offset:5168
	ds_write_b16 v0, v228 offset:6528
	ds_write_b16_d16_hi v0, v228 offset:6800
	ds_write_b16 v0, v229 offset:7072
	ds_write_b16_d16_hi v0, v229 offset:7344
	ds_write_b16 v0, v230 offset:64
	ds_write_b16_d16_hi v0, v230 offset:336
	ds_write_b16 v0, v231 offset:608
	ds_write_b16_d16_hi v0, v231 offset:880
	ds_write_b16 v0, v232 offset:2240
	ds_write_b16_d16_hi v0, v232 offset:2512
	ds_write_b16 v0, v233 offset:2784
	ds_write_b16_d16_hi v0, v233 offset:3056
	ds_write_b16 v0, v234 offset:4416
	ds_write_b16_d16_hi v0, v234 offset:4688
	ds_write_b16 v0, v235 offset:4960
	ds_write_b16_d16_hi v0, v235 offset:5232
	ds_write_b16 v0, v236 offset:6592
	ds_write_b16_d16_hi v0, v236 offset:6864
	ds_write_b16 v0, v237 offset:7136
	ds_write_b16_d16_hi v0, v237 offset:7408
	ds_write_b16 v0, v238 offset:8704
	ds_write_b16_d16_hi v0, v238 offset:8976
	ds_write_b16 v0, v239 offset:9248
	ds_write_b16_d16_hi v0, v239 offset:9520
	ds_write_b16 v0, v240 offset:10880
	ds_write_b16_d16_hi v0, v240 offset:11152
	ds_write_b16 v0, v241 offset:11424
	ds_write_b16_d16_hi v0, v241 offset:11696
	ds_write_b16 v0, v242 offset:13056
	ds_write_b16_d16_hi v0, v242 offset:13328
	ds_write_b16 v0, v243 offset:13600
	ds_write_b16_d16_hi v0, v243 offset:13872
	ds_write_b16 v0, v244 offset:15232
	ds_write_b16_d16_hi v0, v244 offset:15504
	ds_write_b16 v0, v245 offset:15776
	ds_write_b16_d16_hi v0, v245 offset:16048
	ds_write_b16 v0, v246 offset:8768
	ds_write_b16_d16_hi v0, v246 offset:9040
	ds_write_b16 v0, v247 offset:9312
	ds_write_b16_d16_hi v0, v247 offset:9584
	ds_write_b16 v0, v248 offset:10944
	ds_write_b16_d16_hi v0, v248 offset:11216
	ds_write_b16 v0, v249 offset:11488
	ds_write_b16_d16_hi v0, v249 offset:11760
	ds_write_b16 v0, v250 offset:13120
	ds_write_b16_d16_hi v0, v250 offset:13392
	ds_write_b16 v0, v251 offset:13664
	ds_write_b16_d16_hi v0, v251 offset:13936
	ds_write_b16 v0, v252 offset:15296
	ds_write_b16_d16_hi v0, v252 offset:15568
	ds_write_b16 v0, v253 offset:15840
	ds_write_b16_d16_hi v0, v253 offset:16112
	s_waitcnt lgkmcnt(0)
	s_barrier
	ds_read_b128 v[8:11], v1
	ds_read_b128 v[12:15], v1 offset:4352
	ds_read_b128 v[16:19], v1 offset:8704
	ds_read_b128 v[20:23], v1 offset:13056
	ds_read_b128 v[24:27], v1 offset:17408
	ds_read_b128 v[28:31], v1 offset:21760
	ds_read_b128 v[32:35], v1 offset:26112
	ds_read_b128 v[36:39], v1 offset:30464
	s_add_u32 s38, s44, 0x80000
	s_addc_u32 s39, s45, 0
	s_waitcnt lgkmcnt(7)
	global_store_dwordx4 v2, v[8:11], s[38:39]
	s_add_u32 s38, s44, 0xa0000
	s_addc_u32 s39, s45, 0
	s_waitcnt lgkmcnt(6)
	global_store_dwordx4 v2, v[12:15], s[38:39]
	s_add_u32 s38, s44, 0xc0000
	s_addc_u32 s39, s45, 0
	s_waitcnt lgkmcnt(5)
	global_store_dwordx4 v2, v[16:19], s[38:39]
	s_add_u32 s38, s44, 0xe0000
	s_addc_u32 s39, s45, 0
	s_waitcnt lgkmcnt(4)
	global_store_dwordx4 v2, v[20:23], s[38:39]
	s_add_u32 s38, s44, 0x180000
	s_addc_u32 s39, s45, 0
	s_waitcnt lgkmcnt(3)
	global_store_dwordx4 v2, v[24:27], s[38:39]
	s_add_u32 s38, s44, 0x1a0000
	s_addc_u32 s39, s45, 0
	s_waitcnt lgkmcnt(2)
	global_store_dwordx4 v2, v[28:31], s[38:39]
	s_add_u32 s38, s44, 0x1c0000
	s_addc_u32 s39, s45, 0
	s_waitcnt lgkmcnt(1)
	global_store_dwordx4 v2, v[32:35], s[38:39]
	s_add_u32 s38, s44, 0x1e0000
	s_addc_u32 s39, s45, 0
	s_waitcnt lgkmcnt(0)
	global_store_dwordx4 v2, v[36:39], s[38:39]
	s_mov_b32 s43, 0
	s_branch .LBB0_1969
